# snake MFMA order in every GEMM K-loop (all 128 groups of 8), on top of bisection-count + P5 mask rewrites
# baseline (speedup 1.0000x reference)
;     __host__ __device__ bool next(int i, Unit& u) const { const bool ok = StaticOrder::next(i >> 1, u); u.z = i & 1; return ok; }
; #define PG8_STAGE(bufoff, gbase, voff) do { _Pragma("unroll") for (int _i = 0; _i < 2; ++_i) \
;         __builtin_amdgcn_global_load_lds((const unsigned*)((const char*)(gbase) + (voff)[_i]), (LAS unsigned*)(lds + (bufoff) + ldsw + _i * 8192), 16, 0, 0); } while (0)
; #define PG8_LDA(dst, b, h) do { _Pragma("unroll") for (int m = 0; m < 4; ++m) _Pragma("unroll") for (int k = 0; k < 2; ++k) dst[m][k] = *(const LAS bf16x8*)(lds + PG8_SA(b, h) + aoff + m * 2048 + k * 1024); } while (0)
; #define PG8_LDB(dst, b, h) do { _Pragma("unroll") for (int n = 0; n < 2; ++n) _Pragma("unroll") for (int k = 0; k < 2; ++k) dst[n][k] = *(const LAS bf16x8*)(lds + PG8_SB(b, h) + boff + n * 2048 + k * 1024); } while (0)
; #define PG8_WAIT_V(n) asm volatile("s_waitcnt vmcnt(" #n ")" ::: "memory")
; #define PG8_WAIT_L(n) asm volatile("s_waitcnt lgkmcnt(" #n ")" ::: "memory")
; #define PG8_BAR __builtin_amdgcn_s_barrier()
; template <class Epi, class Sched, bool ALIGN_EPI = true, bool SP2 = true>
; __device__ __forceinline__ void gemm_phase(LAS unsigned char* lds, const Gemm g, const Sched& S, const Epi& E) {
;     ...
;         const bool has_next = S.next(ui + 1, nxt);
;         const char* nA = has_next ? PG8_ABASE(nxt) : cA; const char* nB = has_next ? PG8_BBASE(nxt) : cB;
;         for (int t = 0; t < nt; t += 2) {
;             const bool last = (t == nt - 2);
;             const char* a1 = cA + (size_t)(t + 1) * kstep;
;             const char* a2 = last ? nA : cA + (size_t)(t + 2) * kstep; const char* b2 = last ? nB : cB + (size_t)(t + 2) * kstep;
;             const char* a3 = a2 + kstep; const char* b3 = b2 + kstep;
;             if (last && has_next) S.a_ready(nxt);
;             if constexpr (SP2) {
;             PG8_LDB(B0, 0, 0); PG8_LDB(B1, 0, 1); PG8_SCHED; PG8_LDA(At, 0, 0); PG8_STAGE(PG8_SA(1, 1), a1 + hstep, voffA);
;             PG8_WAIT_V(8); PG8_WAIT_L(0); PG8_BAR; PG8_MMA(0, 0, At, B0); PG8_MMA(0, 1, At, B1); PG8_BAR; PG8_SCHED;
;             PG8_LDA(At, 0, 1); PG8_STAGE(PG8_SB(0, 0), b2, voffB); PG8_STAGE(PG8_SB(0, 1), b2 + hstep, voffB); PG8_STAGE(PG8_SA(0, 0), a2, voffA);
;             PG8_WAIT_V(8); PG8_WAIT_L(0); PG8_BAR; PG8_MMA(1, 0, At, B0); PG8_MMA(1, 1, At, B1); PG8_BAR; PG8_SCHED;
.LBB0_451:
	ds_read_b128 v[146:149], v152
	ds_read_b128 v[156:159], v152 offset:1024
	ds_read_b128 v[160:163], v152 offset:2048
	ds_read_b128 v[164:167], v152 offset:3072
	ds_read_b128 v[168:171], v153
	ds_read_b128 v[172:175], v153 offset:1024
	ds_read_b128 v[176:179], v153 offset:2048
	ds_read_b128 v[180:183], v153 offset:3072
	s_add_u32 s22, s20, 0xfffc0080
	s_addc_u32 s23, s21, -1
	s_cmp_eq_u32 s49, 12
	s_cselect_b32 s25, s13, s23
	s_cselect_b32 s24, s45, s22
	s_cselect_b32 s23, s11, s48
	s_cselect_b32 s22, s46, s47
	v_lshl_add_u64 v[216:217], s[20:21], 0, v[138:139]
	s_add_i32 m0, s19, 0xc000
	ds_read_b128 v[184:187], v154
	ds_read_b128 v[188:191], v154 offset:1024
	ds_read_b128 v[192:195], v154 offset:2048
	ds_read_b128 v[196:199], v154 offset:3072
	ds_read_b128 v[200:203], v154 offset:4096
	ds_read_b128 v[204:207], v154 offset:5120
	ds_read_b128 v[208:211], v154 offset:6144
	ds_read_b128 v[212:215], v154 offset:7168
	global_load_lds_dwordx4 v[216:217], off
	v_lshl_add_u64 v[216:217], s[20:21], 0, v[140:141]
	s_add_i32 m0, s19, 0xe000
	s_nop 0
	global_load_lds_dwordx4 v[216:217], off
	s_waitcnt vmcnt(8)
	s_waitcnt lgkmcnt(0)
	s_barrier
	s_setprio 1
	s_waitcnt lgkmcnt(0)
	v_mfma_f32_16x16x32_bf16 v[126:129], v[146:149], v[184:187], v[126:129]
	v_mfma_f32_16x16x32_bf16 v[122:125], v[160:163], v[184:187], v[122:125]
	v_mfma_f32_16x16x32_bf16 v[110:113], v[160:163], v[192:195], v[110:113]
	v_mfma_f32_16x16x32_bf16 v[118:121], v[146:149], v[192:195], v[118:121]
	v_mfma_f32_16x16x32_bf16 v[102:105], v[146:149], v[200:203], v[102:105]
	v_mfma_f32_16x16x32_bf16 v[94:97], v[160:163], v[200:203], v[94:97]
	v_mfma_f32_16x16x32_bf16 v[78:81], v[160:163], v[208:211], v[78:81]
	v_mfma_f32_16x16x32_bf16 v[86:89], v[146:149], v[208:211], v[86:89]
	v_mfma_f32_16x16x32_bf16 v[126:129], v[156:159], v[188:191], v[126:129]
	v_mfma_f32_16x16x32_bf16 v[122:125], v[164:167], v[188:191], v[122:125]
	v_mfma_f32_16x16x32_bf16 v[110:113], v[164:167], v[196:199], v[110:113]
	v_mfma_f32_16x16x32_bf16 v[118:121], v[156:159], v[196:199], v[118:121]
	v_mfma_f32_16x16x32_bf16 v[102:105], v[156:159], v[204:207], v[102:105]
	v_mfma_f32_16x16x32_bf16 v[94:97], v[164:167], v[204:207], v[94:97]
	v_mfma_f32_16x16x32_bf16 v[78:81], v[164:167], v[212:215], v[78:81]
	v_mfma_f32_16x16x32_bf16 v[86:89], v[156:159], v[212:215], v[86:89]
	s_setprio 0
	s_setprio 1
	v_mfma_f32_16x16x32_bf16 v[114:117], v[168:171], v[184:187], v[114:117]
	v_mfma_f32_16x16x32_bf16 v[106:109], v[176:179], v[184:187], v[106:109]
	v_mfma_f32_16x16x32_bf16 v[90:93], v[176:179], v[192:195], v[90:93]
	v_mfma_f32_16x16x32_bf16 v[98:101], v[168:171], v[192:195], v[98:101]
	v_mfma_f32_16x16x32_bf16 v[82:85], v[168:171], v[200:203], v[82:85]
	v_mfma_f32_16x16x32_bf16 v[74:77], v[176:179], v[200:203], v[74:77]
	v_mfma_f32_16x16x32_bf16 v[66:69], v[176:179], v[208:211], v[66:69]
	v_mfma_f32_16x16x32_bf16 v[70:73], v[168:171], v[208:211], v[70:73]
	v_mfma_f32_16x16x32_bf16 v[114:117], v[172:175], v[188:191], v[114:117]
	v_mfma_f32_16x16x32_bf16 v[106:109], v[180:183], v[188:191], v[106:109]
	v_mfma_f32_16x16x32_bf16 v[90:93], v[180:183], v[196:199], v[90:93]
	v_mfma_f32_16x16x32_bf16 v[98:101], v[172:175], v[196:199], v[98:101]
	v_mfma_f32_16x16x32_bf16 v[82:85], v[172:175], v[204:207], v[82:85]
	v_mfma_f32_16x16x32_bf16 v[74:77], v[180:183], v[204:207], v[74:77]
	v_mfma_f32_16x16x32_bf16 v[66:69], v[180:183], v[212:215], v[66:69]
	v_mfma_f32_16x16x32_bf16 v[70:73], v[172:175], v[212:215], v[70:73]
	s_setprio 0
	s_barrier
	s_add_i32 s50, s42, s31
	v_lshl_add_u64 v[216:217], s[22:23], 0, v[132:133]
	s_mov_b32 m0, s50
	ds_read_b128 v[184:187], v154 offset:16384
	ds_read_b128 v[188:191], v154 offset:17408
	ds_read_b128 v[192:195], v154 offset:18432
	ds_read_b128 v[196:199], v154 offset:19456
	ds_read_b128 v[200:203], v154 offset:20480
	ds_read_b128 v[204:207], v154 offset:21504
	ds_read_b128 v[208:211], v154 offset:22528
	ds_read_b128 v[212:215], v154 offset:23552
	global_load_lds_dwordx4 v[216:217], off
	s_add_i32 m0, s50, 0x2000
	s_add_u32 s50, s22, 0x40000
	v_lshl_add_u64 v[218:219], s[22:23], 0, v[136:137]
	s_addc_u32 s51, s23, 0
	s_add_i32 s52, s43, s31
	global_load_lds_dwordx4 v[218:219], off
	v_lshl_add_u64 v[220:221], s[50:51], 0, v[132:133]
	s_mov_b32 m0, s52
	v_lshl_add_u64 v[222:223], s[24:25], 0, v[134:135]
	global_load_lds_dwordx4 v[220:221], off
	v_lshl_add_u64 v[220:221], s[50:51], 0, v[136:137]
	s_add_i32 m0, s52, 0x2000
	s_nop 0
	global_load_lds_dwordx4 v[220:221], off
	v_lshl_add_u64 v[220:221], s[24:25], 0, v[130:131]
	s_mov_b32 m0, s19
	s_nop 0
	global_load_lds_dwordx4 v[220:221], off
	s_mov_b32 m0, s33
	s_nop 0
	global_load_lds_dwordx4 v[222:223], off
	s_waitcnt vmcnt(8)
	s_waitcnt lgkmcnt(0)
	s_barrier
; #define PG8_STAGE(bufoff, gbase, voff) do { _Pragma("unroll") for (int _i = 0; _i < 2; ++_i) \
;         __builtin_amdgcn_global_load_lds((const unsigned*)((const char*)(gbase) + (voff)[_i]), (LAS unsigned*)(lds + (bufoff) + ldsw + _i * 8192), 16, 0, 0); } while (0)
; #define PG8_LDA(dst, b, h) do { _Pragma("unroll") for (int m = 0; m < 4; ++m) _Pragma("unroll") for (int k = 0; k < 2; ++k) dst[m][k] = *(const LAS bf16x8*)(lds + PG8_SA(b, h) + aoff + m * 2048 + k * 1024); } while (0)
; #define PG8_LDB(dst, b, h) do { _Pragma("unroll") for (int n = 0; n < 2; ++n) _Pragma("unroll") for (int k = 0; k < 2; ++k) dst[n][k] = *(const LAS bf16x8*)(lds + PG8_SB(b, h) + boff + n * 2048 + k * 1024); } while (0)
; #define PG8_MMA(ai, bj, At, Bt) do { __builtin_amdgcn_s_setprio(1); _Pragma("unroll") for (int m = 0; m < 4; ++m) _Pragma("unroll") for (int n = 0; n < 2; ++n) _Pragma("unroll") for (int k = 0; k < 2; ++k) \
;         acc[ai][bj][m][n] = __builtin_amdgcn_mfma_f32_16x16x32_bf16(Bt[n][k], At[m][k], acc[ai][bj][m][n], 0, 0, 0); __builtin_amdgcn_s_setprio(0); } while (0)
; #define PG8_WAIT_V(n) asm volatile("s_waitcnt vmcnt(" #n ")" ::: "memory")
; #define PG8_WAIT_L(n) asm volatile("s_waitcnt lgkmcnt(" #n ")" ::: "memory")
; #define PG8_BAR __builtin_amdgcn_s_barrier()
; #define PG8_SCHED __builtin_amdgcn_sched_barrier(0)
; template <class Epi, class Sched, bool ALIGN_EPI = true, bool SP2 = true>
; __device__ __forceinline__ void gemm_phase(LAS unsigned char* lds, const Gemm g, const Sched& S, const Epi& E) {
;     ...
;             PG8_WAIT_V(8); PG8_WAIT_L(0); PG8_BAR; PG8_MMA(1, 0, At, B0); PG8_MMA(1, 1, At, B1); PG8_BAR; PG8_SCHED;
;             PG8_LDB(B0, 1, 0); PG8_LDB(B1, 1, 1); PG8_SCHED; PG8_LDA(At, 1, 0); PG8_STAGE(PG8_SA(0, 1), a2 + hstep, voffA);
;             PG8_WAIT_V(8); PG8_WAIT_L(0); PG8_BAR; PG8_MMA(0, 0, At, B0); PG8_MMA(0, 1, At, B1); PG8_BAR; PG8_SCHED;
	s_setprio 1
	s_waitcnt lgkmcnt(0)
	v_mfma_f32_16x16x32_bf16 v[62:65], v[146:149], v[184:187], v[62:65]
	v_mfma_f32_16x16x32_bf16 v[58:61], v[160:163], v[184:187], v[58:61]
	v_mfma_f32_16x16x32_bf16 v[46:49], v[160:163], v[192:195], v[46:49]
	v_mfma_f32_16x16x32_bf16 v[54:57], v[146:149], v[192:195], v[54:57]
	v_mfma_f32_16x16x32_bf16 v[38:41], v[146:149], v[200:203], v[38:41]
	v_mfma_f32_16x16x32_bf16 v[30:33], v[160:163], v[200:203], v[30:33]
	v_mfma_f32_16x16x32_bf16 v[14:17], v[160:163], v[208:211], v[14:17]
	v_mfma_f32_16x16x32_bf16 v[22:25], v[146:149], v[208:211], v[22:25]
	v_mfma_f32_16x16x32_bf16 v[62:65], v[156:159], v[188:191], v[62:65]
	v_mfma_f32_16x16x32_bf16 v[58:61], v[164:167], v[188:191], v[58:61]
	v_mfma_f32_16x16x32_bf16 v[46:49], v[164:167], v[196:199], v[46:49]
	v_mfma_f32_16x16x32_bf16 v[54:57], v[156:159], v[196:199], v[54:57]
	v_mfma_f32_16x16x32_bf16 v[38:41], v[156:159], v[204:207], v[38:41]
	v_mfma_f32_16x16x32_bf16 v[30:33], v[164:167], v[204:207], v[30:33]
	v_mfma_f32_16x16x32_bf16 v[14:17], v[164:167], v[212:215], v[14:17]
	v_mfma_f32_16x16x32_bf16 v[22:25], v[156:159], v[212:215], v[22:25]
	s_setprio 0
	s_setprio 1
	v_mfma_f32_16x16x32_bf16 v[50:53], v[168:171], v[184:187], v[50:53]
	v_mfma_f32_16x16x32_bf16 v[42:45], v[176:179], v[184:187], v[42:45]
	v_mfma_f32_16x16x32_bf16 v[26:29], v[176:179], v[192:195], v[26:29]
	v_mfma_f32_16x16x32_bf16 v[34:37], v[168:171], v[192:195], v[34:37]
	v_mfma_f32_16x16x32_bf16 v[18:21], v[168:171], v[200:203], v[18:21]
	v_mfma_f32_16x16x32_bf16 v[10:13], v[176:179], v[200:203], v[10:13]
	v_mfma_f32_16x16x32_bf16 v[2:5], v[176:179], v[208:211], v[2:5]
	v_mfma_f32_16x16x32_bf16 v[6:9], v[168:171], v[208:211], v[6:9]
	v_mfma_f32_16x16x32_bf16 v[50:53], v[172:175], v[188:191], v[50:53]
	v_mfma_f32_16x16x32_bf16 v[42:45], v[180:183], v[188:191], v[42:45]
	v_mfma_f32_16x16x32_bf16 v[26:29], v[180:183], v[196:199], v[26:29]
	v_mfma_f32_16x16x32_bf16 v[34:37], v[172:175], v[196:199], v[34:37]
	v_mfma_f32_16x16x32_bf16 v[18:21], v[172:175], v[204:207], v[18:21]
	v_mfma_f32_16x16x32_bf16 v[10:13], v[180:183], v[204:207], v[10:13]
	v_mfma_f32_16x16x32_bf16 v[2:5], v[180:183], v[212:215], v[2:5]
	v_mfma_f32_16x16x32_bf16 v[6:9], v[172:175], v[212:215], v[6:9]
	s_setprio 0
	s_barrier
	s_add_i32 s50, 0, 0x18000
	v_add_u32_e32 v155, s50, v150
	s_add_i32 s51, 0, 0x1c000
	ds_read_b128 v[146:149], v155
	ds_read_b128 v[156:159], v155 offset:1024
	ds_read_b128 v[160:163], v155 offset:2048
	ds_read_b128 v[164:167], v155 offset:3072
	v_add_u32_e32 v155, s51, v150
	ds_read_b128 v[168:171], v155
	ds_read_b128 v[172:175], v155 offset:1024
	ds_read_b128 v[176:179], v155 offset:2048
	ds_read_b128 v[180:183], v155 offset:3072
	s_add_u32 s24, s24, 0x40000
	s_addc_u32 s25, s25, 0
	s_mov_b32 m0, s34
	v_lshl_add_u64 v[224:225], s[24:25], 0, v[130:131]
	ds_read_b128 v[184:187], v154 offset:32768
	ds_read_b128 v[188:191], v154 offset:33792
	ds_read_b128 v[192:195], v154 offset:34816
	ds_read_b128 v[196:199], v154 offset:35840
	ds_read_b128 v[200:203], v154 offset:36864
	ds_read_b128 v[204:207], v154 offset:37888
	ds_read_b128 v[208:211], v154 offset:38912
	ds_read_b128 v[212:215], v154 offset:39936
	global_load_lds_dwordx4 v[224:225], off
	v_lshl_add_u64 v[224:225], s[24:25], 0, v[134:135]
	s_mov_b32 m0, s35
	s_nop 0
	global_load_lds_dwordx4 v[224:225], off
	s_waitcnt vmcnt(8)
	s_waitcnt lgkmcnt(0)
	s_barrier
	s_setprio 1
	s_waitcnt lgkmcnt(0)
	v_mfma_f32_16x16x32_bf16 v[126:129], v[146:149], v[184:187], v[126:129]
	v_mfma_f32_16x16x32_bf16 v[122:125], v[160:163], v[184:187], v[122:125]
	v_mfma_f32_16x16x32_bf16 v[110:113], v[160:163], v[192:195], v[110:113]
	v_mfma_f32_16x16x32_bf16 v[118:121], v[146:149], v[192:195], v[118:121]
	v_mfma_f32_16x16x32_bf16 v[102:105], v[146:149], v[200:203], v[102:105]
	v_mfma_f32_16x16x32_bf16 v[94:97], v[160:163], v[200:203], v[94:97]
	v_mfma_f32_16x16x32_bf16 v[78:81], v[160:163], v[208:211], v[78:81]
	v_mfma_f32_16x16x32_bf16 v[86:89], v[146:149], v[208:211], v[86:89]
	v_mfma_f32_16x16x32_bf16 v[126:129], v[156:159], v[188:191], v[126:129]
	v_mfma_f32_16x16x32_bf16 v[122:125], v[164:167], v[188:191], v[122:125]
	v_mfma_f32_16x16x32_bf16 v[110:113], v[164:167], v[196:199], v[110:113]
	v_mfma_f32_16x16x32_bf16 v[118:121], v[156:159], v[196:199], v[118:121]
	v_mfma_f32_16x16x32_bf16 v[102:105], v[156:159], v[204:207], v[102:105]
	v_mfma_f32_16x16x32_bf16 v[94:97], v[164:167], v[204:207], v[94:97]
	v_mfma_f32_16x16x32_bf16 v[78:81], v[164:167], v[212:215], v[78:81]
	v_mfma_f32_16x16x32_bf16 v[86:89], v[156:159], v[212:215], v[86:89]
	s_setprio 0
	s_setprio 1
	v_mfma_f32_16x16x32_bf16 v[114:117], v[168:171], v[184:187], v[114:117]
	v_mfma_f32_16x16x32_bf16 v[106:109], v[176:179], v[184:187], v[106:109]
	v_mfma_f32_16x16x32_bf16 v[90:93], v[176:179], v[192:195], v[90:93]
	v_mfma_f32_16x16x32_bf16 v[98:101], v[168:171], v[192:195], v[98:101]
	v_mfma_f32_16x16x32_bf16 v[82:85], v[168:171], v[200:203], v[82:85]
	v_mfma_f32_16x16x32_bf16 v[74:77], v[176:179], v[200:203], v[74:77]
	v_mfma_f32_16x16x32_bf16 v[66:69], v[176:179], v[208:211], v[66:69]
	v_mfma_f32_16x16x32_bf16 v[70:73], v[168:171], v[208:211], v[70:73]
	v_mfma_f32_16x16x32_bf16 v[114:117], v[172:175], v[188:191], v[114:117]
	v_mfma_f32_16x16x32_bf16 v[106:109], v[180:183], v[188:191], v[106:109]
	v_mfma_f32_16x16x32_bf16 v[90:93], v[180:183], v[196:199], v[90:93]
	v_mfma_f32_16x16x32_bf16 v[98:101], v[172:175], v[196:199], v[98:101]
	v_mfma_f32_16x16x32_bf16 v[82:85], v[172:175], v[204:207], v[82:85]
	v_mfma_f32_16x16x32_bf16 v[74:77], v[180:183], v[204:207], v[74:77]
	v_mfma_f32_16x16x32_bf16 v[66:69], v[180:183], v[212:215], v[66:69]
	v_mfma_f32_16x16x32_bf16 v[70:73], v[172:175], v[212:215], v[70:73]
	s_setprio 0
	s_barrier
; #define PG8_STAGE(bufoff, gbase, voff) do { _Pragma("unroll") for (int _i = 0; _i < 2; ++_i) \
;         __builtin_amdgcn_global_load_lds((const unsigned*)((const char*)(gbase) + (voff)[_i]), (LAS unsigned*)(lds + (bufoff) + ldsw + _i * 8192), 16, 0, 0); } while (0)
; #define PG8_LDA(dst, b, h) do { _Pragma("unroll") for (int m = 0; m < 4; ++m) _Pragma("unroll") for (int k = 0; k < 2; ++k) dst[m][k] = *(const LAS bf16x8*)(lds + PG8_SA(b, h) + aoff + m * 2048 + k * 1024); } while (0)
; #define PG8_LDB(dst, b, h) do { _Pragma("unroll") for (int n = 0; n < 2; ++n) _Pragma("unroll") for (int k = 0; k < 2; ++k) dst[n][k] = *(const LAS bf16x8*)(lds + PG8_SB(b, h) + boff + n * 2048 + k * 1024); } while (0)
; template <class Epi, class Sched, bool ALIGN_EPI = true, bool SP2 = true>
; __device__ __forceinline__ void gemm_phase(LAS unsigned char* lds, const Gemm g, const Sched& S, const Epi& E) {
;     ...
;         for (int t = 0; t < nt; t += 2) {
;             const bool last = (t == nt - 2);
;             const char* a1 = cA + (size_t)(t + 1) * kstep;
;             const char* a2 = last ? nA : cA + (size_t)(t + 2) * kstep; const char* b2 = last ? nB : cB + (size_t)(t + 2) * kstep;
;             const char* a3 = a2 + kstep; const char* b3 = b2 + kstep;
;             if (last && has_next) S.a_ready(nxt);
;             if constexpr (SP2) {
;             PG8_LDB(B0, 0, 0); PG8_LDB(B1, 0, 1); PG8_SCHED; PG8_LDA(At, 0, 0); PG8_STAGE(PG8_SA(1, 1), a1 + hstep, voffA);
;             PG8_WAIT_V(8); PG8_WAIT_L(0); PG8_BAR; PG8_MMA(0, 0, At, B0); PG8_MMA(0, 1, At, B1); PG8_BAR; PG8_SCHED;
;             PG8_LDA(At, 0, 1); PG8_STAGE(PG8_SB(0, 0), b2, voffB); PG8_STAGE(PG8_SB(0, 1), b2 + hstep, voffB); PG8_STAGE(PG8_SA(0, 0), a2, voffA);
;             PG8_WAIT_V(8); PG8_WAIT_L(0); PG8_BAR; PG8_MMA(1, 0, At, B0); PG8_MMA(1, 1, At, B1); PG8_BAR; PG8_SCHED;
;             PG8_LDB(B0, 1, 0); PG8_LDB(B1, 1, 1); PG8_SCHED; PG8_LDA(At, 1, 0); PG8_STAGE(PG8_SA(0, 1), a2 + hstep, voffA);
;             PG8_WAIT_V(8); PG8_WAIT_L(0); PG8_BAR; PG8_MMA(0, 0, At, B0); PG8_MMA(0, 1, At, B1); PG8_BAR; PG8_SCHED;
;             PG8_LDA(At, 1, 1); PG8_STAGE(PG8_SB(1, 0), b3, voffB); PG8_STAGE(PG8_SB(1, 1), b3 + hstep, voffB); PG8_STAGE(PG8_SA(1, 0), a3, voffA);
;             PG8_WAIT_V(8); PG8_WAIT_L(0); PG8_BAR; PG8_MMA(1, 0, At, B0); PG8_MMA(1, 1, At, B1); PG8_BAR; PG8_SCHED;
	s_add_i32 s24, s50, s31
	v_lshl_add_u64 v[216:217], v[216:217], 0, s[6:7]
	s_mov_b32 m0, s24
	ds_read_b128 v[184:187], v154 offset:49152
	ds_read_b128 v[188:191], v154 offset:50176
	ds_read_b128 v[192:195], v154 offset:51200
	ds_read_b128 v[196:199], v154 offset:52224
	ds_read_b128 v[200:203], v154 offset:53248
	ds_read_b128 v[204:207], v154 offset:54272
	ds_read_b128 v[208:211], v154 offset:55296
	ds_read_b128 v[212:215], v154 offset:56320
	global_load_lds_dwordx4 v[216:217], off
	s_add_i32 m0, s24, 0x2000
	s_add_u32 s22, s22, 0x40080
	v_lshl_add_u64 v[216:217], v[218:219], 0, s[6:7]
	s_addc_u32 s23, s23, 0
	s_add_i32 s24, s51, s31
	global_load_lds_dwordx4 v[216:217], off
	v_lshl_add_u64 v[216:217], s[22:23], 0, v[132:133]
	s_mov_b32 m0, s24
	s_nop 0
	global_load_lds_dwordx4 v[216:217], off
	v_lshl_add_u64 v[216:217], s[22:23], 0, v[136:137]
	s_add_i32 m0, s24, 0x2000
	s_nop 0
	global_load_lds_dwordx4 v[216:217], off
	v_lshl_add_u64 v[216:217], v[220:221], 0, s[6:7]
	s_mov_b32 m0, s39
	s_nop 0
	global_load_lds_dwordx4 v[216:217], off
	v_lshl_add_u64 v[216:217], v[222:223], 0, s[6:7]
	s_mov_b32 m0, s40
	s_nop 0
	global_load_lds_dwordx4 v[216:217], off
	s_waitcnt vmcnt(8)
	s_waitcnt lgkmcnt(0)
	s_barrier
	s_setprio 1
	s_waitcnt lgkmcnt(0)
	v_mfma_f32_16x16x32_bf16 v[62:65], v[146:149], v[184:187], v[62:65]
	v_mfma_f32_16x16x32_bf16 v[58:61], v[160:163], v[184:187], v[58:61]
	v_mfma_f32_16x16x32_bf16 v[46:49], v[160:163], v[192:195], v[46:49]
	v_mfma_f32_16x16x32_bf16 v[54:57], v[146:149], v[192:195], v[54:57]
	v_mfma_f32_16x16x32_bf16 v[38:41], v[146:149], v[200:203], v[38:41]
	v_mfma_f32_16x16x32_bf16 v[30:33], v[160:163], v[200:203], v[30:33]
	v_mfma_f32_16x16x32_bf16 v[14:17], v[160:163], v[208:211], v[14:17]
	v_mfma_f32_16x16x32_bf16 v[22:25], v[146:149], v[208:211], v[22:25]
	v_mfma_f32_16x16x32_bf16 v[62:65], v[156:159], v[188:191], v[62:65]
	v_mfma_f32_16x16x32_bf16 v[58:61], v[164:167], v[188:191], v[58:61]
	v_mfma_f32_16x16x32_bf16 v[46:49], v[164:167], v[196:199], v[46:49]
	v_mfma_f32_16x16x32_bf16 v[54:57], v[156:159], v[196:199], v[54:57]
	v_mfma_f32_16x16x32_bf16 v[38:41], v[156:159], v[204:207], v[38:41]
	v_mfma_f32_16x16x32_bf16 v[30:33], v[164:167], v[204:207], v[30:33]
	v_mfma_f32_16x16x32_bf16 v[14:17], v[164:167], v[212:215], v[14:17]
	v_mfma_f32_16x16x32_bf16 v[22:25], v[156:159], v[212:215], v[22:25]
	s_setprio 0
	s_setprio 1
	v_mfma_f32_16x16x32_bf16 v[50:53], v[168:171], v[184:187], v[50:53]
	v_mfma_f32_16x16x32_bf16 v[42:45], v[176:179], v[184:187], v[42:45]
	v_mfma_f32_16x16x32_bf16 v[26:29], v[176:179], v[192:195], v[26:29]
	v_mfma_f32_16x16x32_bf16 v[34:37], v[168:171], v[192:195], v[34:37]
	v_mfma_f32_16x16x32_bf16 v[18:21], v[168:171], v[200:203], v[18:21]
	v_mfma_f32_16x16x32_bf16 v[10:13], v[176:179], v[200:203], v[10:13]
	v_mfma_f32_16x16x32_bf16 v[2:5], v[176:179], v[208:211], v[2:5]
	v_mfma_f32_16x16x32_bf16 v[6:9], v[168:171], v[208:211], v[6:9]
	v_mfma_f32_16x16x32_bf16 v[50:53], v[172:175], v[188:191], v[50:53]
	v_mfma_f32_16x16x32_bf16 v[42:45], v[180:183], v[188:191], v[42:45]
	v_mfma_f32_16x16x32_bf16 v[26:29], v[180:183], v[196:199], v[26:29]
	v_mfma_f32_16x16x32_bf16 v[34:37], v[172:175], v[196:199], v[34:37]
	v_mfma_f32_16x16x32_bf16 v[18:21], v[172:175], v[204:207], v[18:21]
	v_mfma_f32_16x16x32_bf16 v[10:13], v[180:183], v[204:207], v[10:13]
	v_mfma_f32_16x16x32_bf16 v[2:5], v[180:183], v[212:215], v[2:5]
	v_mfma_f32_16x16x32_bf16 v[6:9], v[172:175], v[212:215], v[6:9]
	s_setprio 0
	s_barrier
	s_add_i32 s49, s49, 2
	s_add_u32 s20, s20, 0x100
	s_addc_u32 s21, s21, 0
	s_add_u32 s47, s47, 0x100
	s_addc_u32 s48, s48, 0
	s_cmp_gt_u32 s49, 13
	s_cbranch_scc0 .LBB0_451
	s_and_b64 vcc, exec, s[8:9]
	s_cbranch_vccz .LBB0_454
	s_barrier

;     __host__ __device__ bool next(int i, Unit& u) const { const bool ok = StaticOrder::next(i >> 1, u); u.z = i & 1; return ok; }
; #define PG8_STAGE(bufoff, gbase, voff) do { _Pragma("unroll") for (int _i = 0; _i < 2; ++_i) \
;         __builtin_amdgcn_global_load_lds((const unsigned*)((const char*)(gbase) + (voff)[_i]), (LAS unsigned*)(lds + (bufoff) + ldsw + _i * 8192), 16, 0, 0); } while (0)
; #define PG8_LDA(dst, b, h) do { _Pragma("unroll") for (int m = 0; m < 4; ++m) _Pragma("unroll") for (int k = 0; k < 2; ++k) dst[m][k] = *(const LAS bf16x8*)(lds + PG8_SA(b, h) + aoff + m * 2048 + k * 1024); } while (0)
; #define PG8_LDB(dst, b, h) do { _Pragma("unroll") for (int n = 0; n < 2; ++n) _Pragma("unroll") for (int k = 0; k < 2; ++k) dst[n][k] = *(const LAS bf16x8*)(lds + PG8_SB(b, h) + boff + n * 2048 + k * 1024); } while (0)
; #define PG8_WAIT_V(n) asm volatile("s_waitcnt vmcnt(" #n ")" ::: "memory")
; #define PG8_WAIT_L(n) asm volatile("s_waitcnt lgkmcnt(" #n ")" ::: "memory")
; #define PG8_BAR __builtin_amdgcn_s_barrier()
; template <class Epi, class Sched, bool ALIGN_EPI = true, bool SP2 = true>
; __device__ __forceinline__ void gemm_phase(LAS unsigned char* lds, const Gemm g, const Sched& S, const Epi& E) {
;     ...
;         const bool has_next = S.next(ui + 1, nxt);
;         const char* nA = has_next ? PG8_ABASE(nxt) : cA; const char* nB = has_next ? PG8_BBASE(nxt) : cB;
;         for (int t = 0; t < nt; t += 2) {
;             const bool last = (t == nt - 2);
;             const char* a1 = cA + (size_t)(t + 1) * kstep;
;             const char* a2 = last ? nA : cA + (size_t)(t + 2) * kstep; const char* b2 = last ? nB : cB + (size_t)(t + 2) * kstep;
;             const char* a3 = a2 + kstep; const char* b3 = b2 + kstep;
;             if (last && has_next) S.a_ready(nxt);
;             if constexpr (SP2) {
;             PG8_LDB(B0, 0, 0); PG8_LDB(B1, 0, 1); PG8_SCHED; PG8_LDA(At, 0, 0); PG8_STAGE(PG8_SA(1, 1), a1 + hstep, voffA);
;             PG8_WAIT_V(8); PG8_WAIT_L(0); PG8_BAR; PG8_MMA(0, 0, At, B0); PG8_MMA(0, 1, At, B1); PG8_BAR; PG8_SCHED;
;             PG8_LDA(At, 0, 1); PG8_STAGE(PG8_SB(0, 0), b2, voffB); PG8_STAGE(PG8_SB(0, 1), b2 + hstep, voffB); PG8_STAGE(PG8_SA(0, 0), a2, voffA);
;             PG8_WAIT_V(8); PG8_WAIT_L(0); PG8_BAR; PG8_MMA(1, 0, At, B0); PG8_MMA(1, 1, At, B1); PG8_BAR; PG8_SCHED;
.LBB0_1460:
	ds_read_b128 v[114:117], v221
	ds_read_b128 v[118:121], v221 offset:1024
	ds_read_b128 v[130:133], v221 offset:2048
	ds_read_b128 v[134:137], v221 offset:3072
	ds_read_b128 v[142:145], v222
	ds_read_b128 v[150:153], v222 offset:1024
	ds_read_b128 v[154:157], v222 offset:2048
	ds_read_b128 v[158:161], v222 offset:3072
	s_add_u32 s36, s34, 0xfff80080
	s_addc_u32 s37, s35, -1
	s_cmp_eq_u32 s64, 28
	s_cselect_b32 s39, s25, s37
	s_cselect_b32 s38, s31, s36
	s_cselect_b32 s37, s23, s63
	s_cselect_b32 s36, s61, s62
	v_lshl_add_u64 v[210:211], s[34:35], 0, v[202:203]
	s_add_i32 m0, s44, 0xc000
	ds_read_b128 v[162:165], v223
	ds_read_b128 v[166:169], v223 offset:1024
	ds_read_b128 v[170:173], v223 offset:2048
	ds_read_b128 v[174:177], v223 offset:3072
	ds_read_b128 v[178:181], v223 offset:4096
	ds_read_b128 v[182:185], v223 offset:5120
	ds_read_b128 v[186:189], v223 offset:6144
	ds_read_b128 v[190:193], v223 offset:7168
	global_load_lds_dwordx4 v[210:211], off
	v_lshl_add_u64 v[210:211], s[34:35], 0, v[204:205]
	s_add_i32 m0, s44, 0xe000
	s_nop 0
	global_load_lds_dwordx4 v[210:211], off
	s_waitcnt vmcnt(8)
	s_waitcnt lgkmcnt(0)
	s_barrier
	s_setprio 1
	s_waitcnt lgkmcnt(0)
	v_mfma_f32_16x16x32_bf16 v[146:149], v[114:117], v[162:165], v[146:149]
	v_mfma_f32_16x16x32_bf16 v[138:141], v[130:133], v[162:165], v[138:141]
	v_mfma_f32_16x16x32_bf16 v[106:109], v[130:133], v[170:173], v[106:109]
	v_mfma_f32_16x16x32_bf16 v[110:113], v[114:117], v[170:173], v[110:113]
	v_mfma_f32_16x16x32_bf16 v[94:97], v[114:117], v[178:181], v[94:97]
	v_mfma_f32_16x16x32_bf16 v[90:93], v[130:133], v[178:181], v[90:93]
	v_mfma_f32_16x16x32_bf16 v[74:77], v[130:133], v[186:189], v[74:77]
	v_mfma_f32_16x16x32_bf16 v[78:81], v[114:117], v[186:189], v[78:81]
	v_mfma_f32_16x16x32_bf16 v[146:149], v[118:121], v[166:169], v[146:149]
	v_mfma_f32_16x16x32_bf16 v[138:141], v[134:137], v[166:169], v[138:141]
	v_mfma_f32_16x16x32_bf16 v[106:109], v[134:137], v[174:177], v[106:109]
	v_mfma_f32_16x16x32_bf16 v[110:113], v[118:121], v[174:177], v[110:113]
	v_mfma_f32_16x16x32_bf16 v[94:97], v[118:121], v[182:185], v[94:97]
	v_mfma_f32_16x16x32_bf16 v[90:93], v[134:137], v[182:185], v[90:93]
	v_mfma_f32_16x16x32_bf16 v[74:77], v[134:137], v[190:193], v[74:77]
	v_mfma_f32_16x16x32_bf16 v[78:81], v[118:121], v[190:193], v[78:81]
	s_setprio 0
	s_setprio 1
	v_mfma_f32_16x16x32_bf16 v[126:129], v[142:145], v[162:165], v[126:129]
	v_mfma_f32_16x16x32_bf16 v[122:125], v[154:157], v[162:165], v[122:125]
	v_mfma_f32_16x16x32_bf16 v[98:101], v[154:157], v[170:173], v[98:101]
	v_mfma_f32_16x16x32_bf16 v[102:105], v[142:145], v[170:173], v[102:105]
	v_mfma_f32_16x16x32_bf16 v[86:89], v[142:145], v[178:181], v[86:89]
	v_mfma_f32_16x16x32_bf16 v[82:85], v[154:157], v[178:181], v[82:85]
	v_mfma_f32_16x16x32_bf16 v[66:69], v[154:157], v[186:189], v[66:69]
	v_mfma_f32_16x16x32_bf16 v[70:73], v[142:145], v[186:189], v[70:73]
	v_mfma_f32_16x16x32_bf16 v[126:129], v[150:153], v[166:169], v[126:129]
	v_mfma_f32_16x16x32_bf16 v[122:125], v[158:161], v[166:169], v[122:125]
	v_mfma_f32_16x16x32_bf16 v[98:101], v[158:161], v[174:177], v[98:101]
	v_mfma_f32_16x16x32_bf16 v[102:105], v[150:153], v[174:177], v[102:105]
	v_mfma_f32_16x16x32_bf16 v[86:89], v[150:153], v[182:185], v[86:89]
	v_mfma_f32_16x16x32_bf16 v[82:85], v[158:161], v[182:185], v[82:85]
	v_mfma_f32_16x16x32_bf16 v[66:69], v[158:161], v[190:193], v[66:69]
	v_mfma_f32_16x16x32_bf16 v[70:73], v[150:153], v[190:193], v[70:73]
	s_setprio 0
	s_barrier
	s_add_i32 s65, s57, s43
	v_lshl_add_u64 v[210:211], s[36:37], 0, v[196:197]
	s_mov_b32 m0, s65
	ds_read_b128 v[162:165], v223 offset:16384
	ds_read_b128 v[166:169], v223 offset:17408
	ds_read_b128 v[170:173], v223 offset:18432
	ds_read_b128 v[174:177], v223 offset:19456
	ds_read_b128 v[178:181], v223 offset:20480
	ds_read_b128 v[182:185], v223 offset:21504
	ds_read_b128 v[186:189], v223 offset:22528
	ds_read_b128 v[190:193], v223 offset:23552
	global_load_lds_dwordx4 v[210:211], off
	s_add_i32 m0, s65, 0x2000
	s_add_u32 s66, s36, 0x80000
	v_lshl_add_u64 v[212:213], s[36:37], 0, v[200:201]
	s_addc_u32 s67, s37, 0
	s_add_i32 s65, s58, s43
	global_load_lds_dwordx4 v[212:213], off
	v_lshl_add_u64 v[214:215], s[66:67], 0, v[196:197]
	s_mov_b32 m0, s65
	v_lshl_add_u64 v[216:217], s[38:39], 0, v[198:199]
	global_load_lds_dwordx4 v[214:215], off
	v_lshl_add_u64 v[214:215], s[66:67], 0, v[200:201]
	s_add_i32 m0, s65, 0x2000
	s_nop 0
	global_load_lds_dwordx4 v[214:215], off
	v_lshl_add_u64 v[214:215], s[38:39], 0, v[194:195]
	s_mov_b32 m0, s44
	s_nop 0
	global_load_lds_dwordx4 v[214:215], off
	s_mov_b32 m0, s45
	s_nop 0
	global_load_lds_dwordx4 v[216:217], off
	s_waitcnt vmcnt(8)
	s_waitcnt lgkmcnt(0)
	s_barrier
; #define PG8_STAGE(bufoff, gbase, voff) do { _Pragma("unroll") for (int _i = 0; _i < 2; ++_i) \
;         __builtin_amdgcn_global_load_lds((const unsigned*)((const char*)(gbase) + (voff)[_i]), (LAS unsigned*)(lds + (bufoff) + ldsw + _i * 8192), 16, 0, 0); } while (0)
; #define PG8_LDA(dst, b, h) do { _Pragma("unroll") for (int m = 0; m < 4; ++m) _Pragma("unroll") for (int k = 0; k < 2; ++k) dst[m][k] = *(const LAS bf16x8*)(lds + PG8_SA(b, h) + aoff + m * 2048 + k * 1024); } while (0)
; #define PG8_LDB(dst, b, h) do { _Pragma("unroll") for (int n = 0; n < 2; ++n) _Pragma("unroll") for (int k = 0; k < 2; ++k) dst[n][k] = *(const LAS bf16x8*)(lds + PG8_SB(b, h) + boff + n * 2048 + k * 1024); } while (0)
; #define PG8_MMA(ai, bj, At, Bt) do { __builtin_amdgcn_s_setprio(1); _Pragma("unroll") for (int m = 0; m < 4; ++m) _Pragma("unroll") for (int n = 0; n < 2; ++n) _Pragma("unroll") for (int k = 0; k < 2; ++k) \
;         acc[ai][bj][m][n] = __builtin_amdgcn_mfma_f32_16x16x32_bf16(Bt[n][k], At[m][k], acc[ai][bj][m][n], 0, 0, 0); __builtin_amdgcn_s_setprio(0); } while (0)
; #define PG8_WAIT_V(n) asm volatile("s_waitcnt vmcnt(" #n ")" ::: "memory")
; #define PG8_WAIT_L(n) asm volatile("s_waitcnt lgkmcnt(" #n ")" ::: "memory")
; #define PG8_BAR __builtin_amdgcn_s_barrier()
; #define PG8_SCHED __builtin_amdgcn_sched_barrier(0)
; template <class Epi, class Sched, bool ALIGN_EPI = true, bool SP2 = true>
; __device__ __forceinline__ void gemm_phase(LAS unsigned char* lds, const Gemm g, const Sched& S, const Epi& E) {
;     ...
;             PG8_WAIT_V(8); PG8_WAIT_L(0); PG8_BAR; PG8_MMA(1, 0, At, B0); PG8_MMA(1, 1, At, B1); PG8_BAR; PG8_SCHED;
;             PG8_LDB(B0, 1, 0); PG8_LDB(B1, 1, 1); PG8_SCHED; PG8_LDA(At, 1, 0); PG8_STAGE(PG8_SA(0, 1), a2 + hstep, voffA);
;             PG8_WAIT_V(8); PG8_WAIT_L(0); PG8_BAR; PG8_MMA(0, 0, At, B0); PG8_MMA(0, 1, At, B1); PG8_BAR; PG8_SCHED;
	s_setprio 1
	s_waitcnt lgkmcnt(0)
	v_mfma_f32_16x16x32_bf16 v[62:65], v[114:117], v[162:165], v[62:65]
	v_mfma_f32_16x16x32_bf16 v[58:61], v[130:133], v[162:165], v[58:61]
	v_mfma_f32_16x16x32_bf16 v[42:45], v[130:133], v[170:173], v[42:45]
	v_mfma_f32_16x16x32_bf16 v[46:49], v[114:117], v[170:173], v[46:49]
	v_mfma_f32_16x16x32_bf16 v[30:33], v[114:117], v[178:181], v[30:33]
	v_mfma_f32_16x16x32_bf16 v[26:29], v[130:133], v[178:181], v[26:29]
	v_mfma_f32_16x16x32_bf16 v[10:13], v[130:133], v[186:189], v[10:13]
	v_mfma_f32_16x16x32_bf16 v[14:17], v[114:117], v[186:189], v[14:17]
	v_mfma_f32_16x16x32_bf16 v[62:65], v[118:121], v[166:169], v[62:65]
	v_mfma_f32_16x16x32_bf16 v[58:61], v[134:137], v[166:169], v[58:61]
	v_mfma_f32_16x16x32_bf16 v[42:45], v[134:137], v[174:177], v[42:45]
	v_mfma_f32_16x16x32_bf16 v[46:49], v[118:121], v[174:177], v[46:49]
	v_mfma_f32_16x16x32_bf16 v[30:33], v[118:121], v[182:185], v[30:33]
	v_mfma_f32_16x16x32_bf16 v[26:29], v[134:137], v[182:185], v[26:29]
	v_mfma_f32_16x16x32_bf16 v[10:13], v[134:137], v[190:193], v[10:13]
	v_mfma_f32_16x16x32_bf16 v[14:17], v[118:121], v[190:193], v[14:17]
	s_setprio 0
	s_setprio 1
	v_mfma_f32_16x16x32_bf16 v[54:57], v[142:145], v[162:165], v[54:57]
	v_mfma_f32_16x16x32_bf16 v[50:53], v[154:157], v[162:165], v[50:53]
	v_mfma_f32_16x16x32_bf16 v[34:37], v[154:157], v[170:173], v[34:37]
	v_mfma_f32_16x16x32_bf16 v[38:41], v[142:145], v[170:173], v[38:41]
	v_mfma_f32_16x16x32_bf16 v[22:25], v[142:145], v[178:181], v[22:25]
	v_mfma_f32_16x16x32_bf16 v[18:21], v[154:157], v[178:181], v[18:21]
	v_mfma_f32_16x16x32_bf16 v[2:5], v[154:157], v[186:189], v[2:5]
	v_mfma_f32_16x16x32_bf16 v[6:9], v[142:145], v[186:189], v[6:9]
	v_mfma_f32_16x16x32_bf16 v[54:57], v[150:153], v[166:169], v[54:57]
	v_mfma_f32_16x16x32_bf16 v[50:53], v[158:161], v[166:169], v[50:53]
	v_mfma_f32_16x16x32_bf16 v[34:37], v[158:161], v[174:177], v[34:37]
	v_mfma_f32_16x16x32_bf16 v[38:41], v[150:153], v[174:177], v[38:41]
	v_mfma_f32_16x16x32_bf16 v[22:25], v[150:153], v[182:185], v[22:25]
	v_mfma_f32_16x16x32_bf16 v[18:21], v[158:161], v[182:185], v[18:21]
	v_mfma_f32_16x16x32_bf16 v[2:5], v[158:161], v[190:193], v[2:5]
	v_mfma_f32_16x16x32_bf16 v[6:9], v[150:153], v[190:193], v[6:9]
	s_setprio 0
	s_barrier
	s_add_i32 s65, 0, 0x18000
	s_add_i32 s66, 0, 0x1c000
	v_add_u32_e32 v134, s65, v219
	v_add_u32_e32 v158, s66, v219
	ds_read_b128 v[114:117], v134
	ds_read_b128 v[118:121], v134 offset:1024
	ds_read_b128 v[130:133], v134 offset:2048
	ds_read_b128 v[134:137], v134 offset:3072
	ds_read_b128 v[142:145], v158
	ds_read_b128 v[150:153], v158 offset:1024
	ds_read_b128 v[154:157], v158 offset:2048
	ds_read_b128 v[158:161], v158 offset:3072
	s_add_u32 s38, s38, 0x80000
	s_addc_u32 s39, s39, 0
	s_mov_b32 m0, s46
	v_lshl_add_u64 v[224:225], s[38:39], 0, v[194:195]
	ds_read_b128 v[162:165], v223 offset:32768
	ds_read_b128 v[166:169], v223 offset:33792
	ds_read_b128 v[170:173], v223 offset:34816
	ds_read_b128 v[174:177], v223 offset:35840
	ds_read_b128 v[178:181], v223 offset:36864
	ds_read_b128 v[182:185], v223 offset:37888
	ds_read_b128 v[186:189], v223 offset:38912
	ds_read_b128 v[190:193], v223 offset:39936
	global_load_lds_dwordx4 v[224:225], off
	v_lshl_add_u64 v[224:225], s[38:39], 0, v[198:199]
	s_mov_b32 m0, s47
	s_nop 0
	global_load_lds_dwordx4 v[224:225], off
	s_waitcnt vmcnt(8)
	s_waitcnt lgkmcnt(0)
	s_barrier
	s_setprio 1
	s_waitcnt lgkmcnt(0)
	v_mfma_f32_16x16x32_bf16 v[146:149], v[114:117], v[162:165], v[146:149]
	v_mfma_f32_16x16x32_bf16 v[138:141], v[130:133], v[162:165], v[138:141]
	v_mfma_f32_16x16x32_bf16 v[106:109], v[130:133], v[170:173], v[106:109]
	v_mfma_f32_16x16x32_bf16 v[110:113], v[114:117], v[170:173], v[110:113]
	v_mfma_f32_16x16x32_bf16 v[94:97], v[114:117], v[178:181], v[94:97]
	v_mfma_f32_16x16x32_bf16 v[90:93], v[130:133], v[178:181], v[90:93]
	v_mfma_f32_16x16x32_bf16 v[74:77], v[130:133], v[186:189], v[74:77]
	v_mfma_f32_16x16x32_bf16 v[78:81], v[114:117], v[186:189], v[78:81]
	v_mfma_f32_16x16x32_bf16 v[146:149], v[118:121], v[166:169], v[146:149]
	v_mfma_f32_16x16x32_bf16 v[138:141], v[134:137], v[166:169], v[138:141]
	v_mfma_f32_16x16x32_bf16 v[106:109], v[134:137], v[174:177], v[106:109]
	v_mfma_f32_16x16x32_bf16 v[110:113], v[118:121], v[174:177], v[110:113]
	v_mfma_f32_16x16x32_bf16 v[94:97], v[118:121], v[182:185], v[94:97]
	v_mfma_f32_16x16x32_bf16 v[90:93], v[134:137], v[182:185], v[90:93]
	v_mfma_f32_16x16x32_bf16 v[74:77], v[134:137], v[190:193], v[74:77]
	v_mfma_f32_16x16x32_bf16 v[78:81], v[118:121], v[190:193], v[78:81]
	s_setprio 0
	s_setprio 1
	v_mfma_f32_16x16x32_bf16 v[126:129], v[142:145], v[162:165], v[126:129]
	v_mfma_f32_16x16x32_bf16 v[122:125], v[154:157], v[162:165], v[122:125]
	v_mfma_f32_16x16x32_bf16 v[98:101], v[154:157], v[170:173], v[98:101]
	v_mfma_f32_16x16x32_bf16 v[102:105], v[142:145], v[170:173], v[102:105]
	v_mfma_f32_16x16x32_bf16 v[86:89], v[142:145], v[178:181], v[86:89]
	v_mfma_f32_16x16x32_bf16 v[82:85], v[154:157], v[178:181], v[82:85]
	v_mfma_f32_16x16x32_bf16 v[66:69], v[154:157], v[186:189], v[66:69]
	v_mfma_f32_16x16x32_bf16 v[70:73], v[142:145], v[186:189], v[70:73]
	v_mfma_f32_16x16x32_bf16 v[126:129], v[150:153], v[166:169], v[126:129]
	v_mfma_f32_16x16x32_bf16 v[122:125], v[158:161], v[166:169], v[122:125]
	v_mfma_f32_16x16x32_bf16 v[98:101], v[158:161], v[174:177], v[98:101]
	v_mfma_f32_16x16x32_bf16 v[102:105], v[150:153], v[174:177], v[102:105]
	v_mfma_f32_16x16x32_bf16 v[86:89], v[150:153], v[182:185], v[86:89]
	v_mfma_f32_16x16x32_bf16 v[82:85], v[158:161], v[182:185], v[82:85]
	v_mfma_f32_16x16x32_bf16 v[66:69], v[158:161], v[190:193], v[66:69]
	v_mfma_f32_16x16x32_bf16 v[70:73], v[150:153], v[190:193], v[70:73]
	s_setprio 0
	s_barrier
; #define PG8_STAGE(bufoff, gbase, voff) do { _Pragma("unroll") for (int _i = 0; _i < 2; ++_i) \
;         __builtin_amdgcn_global_load_lds((const unsigned*)((const char*)(gbase) + (voff)[_i]), (LAS unsigned*)(lds + (bufoff) + ldsw + _i * 8192), 16, 0, 0); } while (0)
; #define PG8_LDA(dst, b, h) do { _Pragma("unroll") for (int m = 0; m < 4; ++m) _Pragma("unroll") for (int k = 0; k < 2; ++k) dst[m][k] = *(const LAS bf16x8*)(lds + PG8_SA(b, h) + aoff + m * 2048 + k * 1024); } while (0)
; #define PG8_LDB(dst, b, h) do { _Pragma("unroll") for (int n = 0; n < 2; ++n) _Pragma("unroll") for (int k = 0; k < 2; ++k) dst[n][k] = *(const LAS bf16x8*)(lds + PG8_SB(b, h) + boff + n * 2048 + k * 1024); } while (0)
; template <class Epi, class Sched, bool ALIGN_EPI = true, bool SP2 = true>
; __device__ __forceinline__ void gemm_phase(LAS unsigned char* lds, const Gemm g, const Sched& S, const Epi& E) {
;     ...
;         for (int t = 0; t < nt; t += 2) {
;             const bool last = (t == nt - 2);
;             const char* a1 = cA + (size_t)(t + 1) * kstep;
;             const char* a2 = last ? nA : cA + (size_t)(t + 2) * kstep; const char* b2 = last ? nB : cB + (size_t)(t + 2) * kstep;
;             const char* a3 = a2 + kstep; const char* b3 = b2 + kstep;
;             if (last && has_next) S.a_ready(nxt);
;             if constexpr (SP2) {
;             PG8_LDB(B0, 0, 0); PG8_LDB(B1, 0, 1); PG8_SCHED; PG8_LDA(At, 0, 0); PG8_STAGE(PG8_SA(1, 1), a1 + hstep, voffA);
;             PG8_WAIT_V(8); PG8_WAIT_L(0); PG8_BAR; PG8_MMA(0, 0, At, B0); PG8_MMA(0, 1, At, B1); PG8_BAR; PG8_SCHED;
;             PG8_LDA(At, 0, 1); PG8_STAGE(PG8_SB(0, 0), b2, voffB); PG8_STAGE(PG8_SB(0, 1), b2 + hstep, voffB); PG8_STAGE(PG8_SA(0, 0), a2, voffA);
;             PG8_WAIT_V(8); PG8_WAIT_L(0); PG8_BAR; PG8_MMA(1, 0, At, B0); PG8_MMA(1, 1, At, B1); PG8_BAR; PG8_SCHED;
;             PG8_LDB(B0, 1, 0); PG8_LDB(B1, 1, 1); PG8_SCHED; PG8_LDA(At, 1, 0); PG8_STAGE(PG8_SA(0, 1), a2 + hstep, voffA);
;             PG8_WAIT_V(8); PG8_WAIT_L(0); PG8_BAR; PG8_MMA(0, 0, At, B0); PG8_MMA(0, 1, At, B1); PG8_BAR; PG8_SCHED;
;             PG8_LDA(At, 1, 1); PG8_STAGE(PG8_SB(1, 0), b3, voffB); PG8_STAGE(PG8_SB(1, 1), b3 + hstep, voffB); PG8_STAGE(PG8_SA(1, 0), a3, voffA);
;             PG8_WAIT_V(8); PG8_WAIT_L(0); PG8_BAR; PG8_MMA(1, 0, At, B0); PG8_MMA(1, 1, At, B1); PG8_BAR; PG8_SCHED;
	s_add_i32 s38, s65, s43
	v_lshl_add_u64 v[210:211], v[210:211], 0, s[12:13]
	s_mov_b32 m0, s38
	ds_read_b128 v[162:165], v223 offset:49152
	ds_read_b128 v[166:169], v223 offset:50176
	ds_read_b128 v[170:173], v223 offset:51200
	ds_read_b128 v[174:177], v223 offset:52224
	ds_read_b128 v[178:181], v223 offset:53248
	ds_read_b128 v[182:185], v223 offset:54272
	ds_read_b128 v[186:189], v223 offset:55296
	ds_read_b128 v[190:193], v223 offset:56320
	global_load_lds_dwordx4 v[210:211], off
	s_add_i32 m0, s38, 0x2000
	s_add_u32 s36, s36, 0x80080
	v_lshl_add_u64 v[210:211], v[212:213], 0, s[12:13]
	s_addc_u32 s37, s37, 0
	s_add_i32 s38, s66, s43
	global_load_lds_dwordx4 v[210:211], off
	v_lshl_add_u64 v[210:211], s[36:37], 0, v[196:197]
	s_mov_b32 m0, s38
	s_nop 0
	global_load_lds_dwordx4 v[210:211], off
	v_lshl_add_u64 v[210:211], s[36:37], 0, v[200:201]
	s_add_i32 m0, s38, 0x2000
	s_nop 0
	global_load_lds_dwordx4 v[210:211], off
	v_lshl_add_u64 v[210:211], v[214:215], 0, s[12:13]
	s_mov_b32 m0, s54
	s_nop 0
	global_load_lds_dwordx4 v[210:211], off
	v_lshl_add_u64 v[210:211], v[216:217], 0, s[12:13]
	s_mov_b32 m0, s55
	s_nop 0
	global_load_lds_dwordx4 v[210:211], off
	s_waitcnt vmcnt(8)
	s_waitcnt lgkmcnt(0)
	s_barrier
	s_setprio 1
	s_waitcnt lgkmcnt(0)
	v_mfma_f32_16x16x32_bf16 v[62:65], v[114:117], v[162:165], v[62:65]
	v_mfma_f32_16x16x32_bf16 v[58:61], v[130:133], v[162:165], v[58:61]
	v_mfma_f32_16x16x32_bf16 v[42:45], v[130:133], v[170:173], v[42:45]
	v_mfma_f32_16x16x32_bf16 v[46:49], v[114:117], v[170:173], v[46:49]
	v_mfma_f32_16x16x32_bf16 v[30:33], v[114:117], v[178:181], v[30:33]
	v_mfma_f32_16x16x32_bf16 v[26:29], v[130:133], v[178:181], v[26:29]
	v_mfma_f32_16x16x32_bf16 v[10:13], v[130:133], v[186:189], v[10:13]
	v_mfma_f32_16x16x32_bf16 v[14:17], v[114:117], v[186:189], v[14:17]
	v_mfma_f32_16x16x32_bf16 v[62:65], v[118:121], v[166:169], v[62:65]
	v_mfma_f32_16x16x32_bf16 v[58:61], v[134:137], v[166:169], v[58:61]
	v_mfma_f32_16x16x32_bf16 v[42:45], v[134:137], v[174:177], v[42:45]
	v_mfma_f32_16x16x32_bf16 v[46:49], v[118:121], v[174:177], v[46:49]
	v_mfma_f32_16x16x32_bf16 v[30:33], v[118:121], v[182:185], v[30:33]
	v_mfma_f32_16x16x32_bf16 v[26:29], v[134:137], v[182:185], v[26:29]
	v_mfma_f32_16x16x32_bf16 v[10:13], v[134:137], v[190:193], v[10:13]
	v_mfma_f32_16x16x32_bf16 v[14:17], v[118:121], v[190:193], v[14:17]
	s_setprio 0
	s_setprio 1
	v_mfma_f32_16x16x32_bf16 v[54:57], v[142:145], v[162:165], v[54:57]
	v_mfma_f32_16x16x32_bf16 v[50:53], v[154:157], v[162:165], v[50:53]
	v_mfma_f32_16x16x32_bf16 v[34:37], v[154:157], v[170:173], v[34:37]
	v_mfma_f32_16x16x32_bf16 v[38:41], v[142:145], v[170:173], v[38:41]
	v_mfma_f32_16x16x32_bf16 v[22:25], v[142:145], v[178:181], v[22:25]
	v_mfma_f32_16x16x32_bf16 v[18:21], v[154:157], v[178:181], v[18:21]
	v_mfma_f32_16x16x32_bf16 v[2:5], v[154:157], v[186:189], v[2:5]
	v_mfma_f32_16x16x32_bf16 v[6:9], v[142:145], v[186:189], v[6:9]
	v_mfma_f32_16x16x32_bf16 v[54:57], v[150:153], v[166:169], v[54:57]
	v_mfma_f32_16x16x32_bf16 v[50:53], v[158:161], v[166:169], v[50:53]
	v_mfma_f32_16x16x32_bf16 v[34:37], v[158:161], v[174:177], v[34:37]
	v_mfma_f32_16x16x32_bf16 v[38:41], v[150:153], v[174:177], v[38:41]
	v_mfma_f32_16x16x32_bf16 v[22:25], v[150:153], v[182:185], v[22:25]
	v_mfma_f32_16x16x32_bf16 v[18:21], v[158:161], v[182:185], v[18:21]
	v_mfma_f32_16x16x32_bf16 v[2:5], v[158:161], v[190:193], v[2:5]
	v_mfma_f32_16x16x32_bf16 v[6:9], v[150:153], v[190:193], v[6:9]
	s_setprio 0
	s_barrier
	s_add_i32 s64, s64, 2
	s_add_u32 s34, s34, 0x100
	s_addc_u32 s35, s35, 0
	s_add_u32 s62, s62, 0x100
	s_addc_u32 s63, s63, 0
	s_cmp_gt_u32 s64, 29
	s_cbranch_scc0 .LBB0_1460
	s_and_b64 vcc, exec, s[14:15]
	s_cbranch_vccz .LBB0_1463
	s_barrier

;     __host__ __device__ bool next(int i, Unit& u) const { const bool ok = StaticOrder::next(i >> 1, u); u.z = i & 1; return ok; }
; #define PG8_STAGE(bufoff, gbase, voff) do { _Pragma("unroll") for (int _i = 0; _i < 2; ++_i) \
;         __builtin_amdgcn_global_load_lds((const unsigned*)((const char*)(gbase) + (voff)[_i]), (LAS unsigned*)(lds + (bufoff) + ldsw + _i * 8192), 16, 0, 0); } while (0)
; #define PG8_LDA(dst, b, h) do { _Pragma("unroll") for (int m = 0; m < 4; ++m) _Pragma("unroll") for (int k = 0; k < 2; ++k) dst[m][k] = *(const LAS bf16x8*)(lds + PG8_SA(b, h) + aoff + m * 2048 + k * 1024); } while (0)
; #define PG8_LDB(dst, b, h) do { _Pragma("unroll") for (int n = 0; n < 2; ++n) _Pragma("unroll") for (int k = 0; k < 2; ++k) dst[n][k] = *(const LAS bf16x8*)(lds + PG8_SB(b, h) + boff + n * 2048 + k * 1024); } while (0)
; #define PG8_WAIT_V(n) asm volatile("s_waitcnt vmcnt(" #n ")" ::: "memory")
; #define PG8_WAIT_L(n) asm volatile("s_waitcnt lgkmcnt(" #n ")" ::: "memory")
; #define PG8_BAR __builtin_amdgcn_s_barrier()
; template <class Epi, class Sched, bool ALIGN_EPI = true, bool SP2 = true>
; __device__ __forceinline__ void gemm_phase(LAS unsigned char* lds, const Gemm g, const Sched& S, const Epi& E) {
;     ...
;         const bool has_next = S.next(ui + 1, nxt);
;         const char* nA = has_next ? PG8_ABASE(nxt) : cA; const char* nB = has_next ? PG8_BBASE(nxt) : cB;
;         for (int t = 0; t < nt; t += 2) {
;             const bool last = (t == nt - 2);
;             const char* a1 = cA + (size_t)(t + 1) * kstep;
;             const char* a2 = last ? nA : cA + (size_t)(t + 2) * kstep; const char* b2 = last ? nB : cB + (size_t)(t + 2) * kstep;
;             const char* a3 = a2 + kstep; const char* b3 = b2 + kstep;
;             if (last && has_next) S.a_ready(nxt);
;             if constexpr (SP2) {
;             PG8_LDB(B0, 0, 0); PG8_LDB(B1, 0, 1); PG8_SCHED; PG8_LDA(At, 0, 0); PG8_STAGE(PG8_SA(1, 1), a1 + hstep, voffA);
;             PG8_WAIT_V(8); PG8_WAIT_L(0); PG8_BAR; PG8_MMA(0, 0, At, B0); PG8_MMA(0, 1, At, B1); PG8_BAR; PG8_SCHED;
;             PG8_LDA(At, 0, 1); PG8_STAGE(PG8_SB(0, 0), b2, voffB); PG8_STAGE(PG8_SB(0, 1), b2 + hstep, voffB); PG8_STAGE(PG8_SA(0, 0), a2, voffA);
;             PG8_WAIT_V(8); PG8_WAIT_L(0); PG8_BAR; PG8_MMA(1, 0, At, B0); PG8_MMA(1, 1, At, B1); PG8_BAR; PG8_SCHED;
.LBB0_1639:
	ds_read_b128 v[130:133], v203
	ds_read_b128 v[134:137], v203 offset:1024
	ds_read_b128 v[138:141], v203 offset:2048
	ds_read_b128 v[142:145], v203 offset:3072
	ds_read_b128 v[146:149], v204
	ds_read_b128 v[150:153], v204 offset:1024
	ds_read_b128 v[154:157], v204 offset:2048
	ds_read_b128 v[158:161], v204 offset:3072
	s_add_u32 s54, s52, 0xfff00080
	s_addc_u32 s55, s53, -1
	s_cmp_eq_u32 s74, 60
	s_cselect_b32 s57, s43, s55
	s_cselect_b32 s56, s49, s54
	s_cselect_b32 s55, s41, s73
	s_cselect_b32 s54, s71, s72
	v_lshl_add_u64 v[198:199], s[52:53], 0, v[186:187]
	s_add_i32 m0, s51, 0xc000
	ds_read_b128 v[162:165], v205
	ds_read_b128 v[166:169], v205 offset:1024
	ds_read_b128 v[170:173], v205 offset:2048
	ds_read_b128 v[174:177], v205 offset:3072
	ds_read_b128 v[194:197], v205 offset:4096
	ds_read_b128 v[208:211], v205 offset:5120
	ds_read_b128 v[212:215], v205 offset:6144
	ds_read_b128 v[216:219], v205 offset:7168
	global_load_lds_dwordx4 v[198:199], off
	v_lshl_add_u64 v[198:199], s[52:53], 0, v[188:189]
	s_add_i32 m0, s51, 0xe000
	s_nop 0
	global_load_lds_dwordx4 v[198:199], off
	s_waitcnt vmcnt(8)
	s_waitcnt lgkmcnt(0)
	s_barrier
	s_setprio 1
	s_waitcnt lgkmcnt(0)
	v_mfma_f32_16x16x32_bf16 v[126:129], v[130:133], v[162:165], v[126:129]
	v_mfma_f32_16x16x32_bf16 v[122:125], v[138:141], v[162:165], v[122:125]
	v_mfma_f32_16x16x32_bf16 v[106:109], v[138:141], v[170:173], v[106:109]
	v_mfma_f32_16x16x32_bf16 v[110:113], v[130:133], v[170:173], v[110:113]
	v_mfma_f32_16x16x32_bf16 v[94:97], v[130:133], v[194:197], v[94:97]
	v_mfma_f32_16x16x32_bf16 v[90:93], v[138:141], v[194:197], v[90:93]
	v_mfma_f32_16x16x32_bf16 v[74:77], v[138:141], v[212:215], v[74:77]
	v_mfma_f32_16x16x32_bf16 v[78:81], v[130:133], v[212:215], v[78:81]
	v_mfma_f32_16x16x32_bf16 v[126:129], v[134:137], v[166:169], v[126:129]
	v_mfma_f32_16x16x32_bf16 v[122:125], v[142:145], v[166:169], v[122:125]
	v_mfma_f32_16x16x32_bf16 v[106:109], v[142:145], v[174:177], v[106:109]
	v_mfma_f32_16x16x32_bf16 v[110:113], v[134:137], v[174:177], v[110:113]
	v_mfma_f32_16x16x32_bf16 v[94:97], v[134:137], v[208:211], v[94:97]
	v_mfma_f32_16x16x32_bf16 v[90:93], v[142:145], v[208:211], v[90:93]
	v_mfma_f32_16x16x32_bf16 v[74:77], v[142:145], v[216:219], v[74:77]
	v_mfma_f32_16x16x32_bf16 v[78:81], v[134:137], v[216:219], v[78:81]
	s_setprio 0
	s_setprio 1
	v_mfma_f32_16x16x32_bf16 v[118:121], v[146:149], v[162:165], v[118:121]
	v_mfma_f32_16x16x32_bf16 v[114:117], v[154:157], v[162:165], v[114:117]
	v_mfma_f32_16x16x32_bf16 v[98:101], v[154:157], v[170:173], v[98:101]
	v_mfma_f32_16x16x32_bf16 v[102:105], v[146:149], v[170:173], v[102:105]
	v_mfma_f32_16x16x32_bf16 v[86:89], v[146:149], v[194:197], v[86:89]
	v_mfma_f32_16x16x32_bf16 v[82:85], v[154:157], v[194:197], v[82:85]
	v_mfma_f32_16x16x32_bf16 v[66:69], v[154:157], v[212:215], v[66:69]
	v_mfma_f32_16x16x32_bf16 v[70:73], v[146:149], v[212:215], v[70:73]
	v_mfma_f32_16x16x32_bf16 v[118:121], v[150:153], v[166:169], v[118:121]
	v_mfma_f32_16x16x32_bf16 v[114:117], v[158:161], v[166:169], v[114:117]
	v_mfma_f32_16x16x32_bf16 v[98:101], v[158:161], v[174:177], v[98:101]
	v_mfma_f32_16x16x32_bf16 v[102:105], v[150:153], v[174:177], v[102:105]
	v_mfma_f32_16x16x32_bf16 v[86:89], v[150:153], v[208:211], v[86:89]
	v_mfma_f32_16x16x32_bf16 v[82:85], v[158:161], v[208:211], v[82:85]
	v_mfma_f32_16x16x32_bf16 v[66:69], v[158:161], v[216:219], v[66:69]
	v_mfma_f32_16x16x32_bf16 v[70:73], v[150:153], v[216:219], v[70:73]
	s_setprio 0
	s_barrier
	s_add_i32 s75, s66, s33
	v_lshl_add_u64 v[198:199], s[54:55], 0, v[180:181]
	s_mov_b32 m0, s75
	ds_read_b128 v[162:165], v205 offset:16384
	ds_read_b128 v[166:169], v205 offset:17408
	ds_read_b128 v[170:173], v205 offset:18432
	ds_read_b128 v[174:177], v205 offset:19456
	ds_read_b128 v[194:197], v205 offset:20480
	ds_read_b128 v[208:211], v205 offset:21504
	ds_read_b128 v[212:215], v205 offset:22528
	ds_read_b128 v[216:219], v205 offset:23552
	global_load_lds_dwordx4 v[198:199], off
	s_add_i32 m0, s75, 0x2000
	s_add_u32 s76, s54, 0x100000
	v_lshl_add_u64 v[220:221], s[54:55], 0, v[184:185]
	s_addc_u32 s77, s55, 0
	s_add_i32 s75, s67, s33
	global_load_lds_dwordx4 v[220:221], off
	v_lshl_add_u64 v[222:223], s[76:77], 0, v[180:181]
	s_mov_b32 m0, s75
	v_lshl_add_u64 v[224:225], s[56:57], 0, v[182:183]
	global_load_lds_dwordx4 v[222:223], off
	v_lshl_add_u64 v[222:223], s[76:77], 0, v[184:185]
	s_add_i32 m0, s75, 0x2000
	s_nop 0
	global_load_lds_dwordx4 v[222:223], off
	v_lshl_add_u64 v[222:223], s[56:57], 0, v[178:179]
	s_mov_b32 m0, s51
	s_nop 0
	global_load_lds_dwordx4 v[222:223], off
	s_mov_b32 m0, s58
	s_nop 0
	global_load_lds_dwordx4 v[224:225], off
	s_waitcnt vmcnt(8)
	s_waitcnt lgkmcnt(0)
	s_barrier
; #define PG8_STAGE(bufoff, gbase, voff) do { _Pragma("unroll") for (int _i = 0; _i < 2; ++_i) \
;         __builtin_amdgcn_global_load_lds((const unsigned*)((const char*)(gbase) + (voff)[_i]), (LAS unsigned*)(lds + (bufoff) + ldsw + _i * 8192), 16, 0, 0); } while (0)
; #define PG8_LDA(dst, b, h) do { _Pragma("unroll") for (int m = 0; m < 4; ++m) _Pragma("unroll") for (int k = 0; k < 2; ++k) dst[m][k] = *(const LAS bf16x8*)(lds + PG8_SA(b, h) + aoff + m * 2048 + k * 1024); } while (0)
; #define PG8_LDB(dst, b, h) do { _Pragma("unroll") for (int n = 0; n < 2; ++n) _Pragma("unroll") for (int k = 0; k < 2; ++k) dst[n][k] = *(const LAS bf16x8*)(lds + PG8_SB(b, h) + boff + n * 2048 + k * 1024); } while (0)
; #define PG8_MMA(ai, bj, At, Bt) do { __builtin_amdgcn_s_setprio(1); _Pragma("unroll") for (int m = 0; m < 4; ++m) _Pragma("unroll") for (int n = 0; n < 2; ++n) _Pragma("unroll") for (int k = 0; k < 2; ++k) \
;         acc[ai][bj][m][n] = __builtin_amdgcn_mfma_f32_16x16x32_bf16(Bt[n][k], At[m][k], acc[ai][bj][m][n], 0, 0, 0); __builtin_amdgcn_s_setprio(0); } while (0)
; #define PG8_WAIT_V(n) asm volatile("s_waitcnt vmcnt(" #n ")" ::: "memory")
; #define PG8_WAIT_L(n) asm volatile("s_waitcnt lgkmcnt(" #n ")" ::: "memory")
; #define PG8_BAR __builtin_amdgcn_s_barrier()
; #define PG8_SCHED __builtin_amdgcn_sched_barrier(0)
; template <class Epi, class Sched, bool ALIGN_EPI = true, bool SP2 = true>
; __device__ __forceinline__ void gemm_phase(LAS unsigned char* lds, const Gemm g, const Sched& S, const Epi& E) {
;     ...
;             PG8_WAIT_V(8); PG8_WAIT_L(0); PG8_BAR; PG8_MMA(1, 0, At, B0); PG8_MMA(1, 1, At, B1); PG8_BAR; PG8_SCHED;
;             PG8_LDB(B0, 1, 0); PG8_LDB(B1, 1, 1); PG8_SCHED; PG8_LDA(At, 1, 0); PG8_STAGE(PG8_SA(0, 1), a2 + hstep, voffA);
;             PG8_WAIT_V(8); PG8_WAIT_L(0); PG8_BAR; PG8_MMA(0, 0, At, B0); PG8_MMA(0, 1, At, B1); PG8_BAR; PG8_SCHED;
	s_setprio 1
	s_waitcnt lgkmcnt(0)
	v_mfma_f32_16x16x32_bf16 v[62:65], v[130:133], v[162:165], v[62:65]
	v_mfma_f32_16x16x32_bf16 v[58:61], v[138:141], v[162:165], v[58:61]
	v_mfma_f32_16x16x32_bf16 v[42:45], v[138:141], v[170:173], v[42:45]
	v_mfma_f32_16x16x32_bf16 v[46:49], v[130:133], v[170:173], v[46:49]
	v_mfma_f32_16x16x32_bf16 v[30:33], v[130:133], v[194:197], v[30:33]
	v_mfma_f32_16x16x32_bf16 v[26:29], v[138:141], v[194:197], v[26:29]
	v_mfma_f32_16x16x32_bf16 v[10:13], v[138:141], v[212:215], v[10:13]
	v_mfma_f32_16x16x32_bf16 v[14:17], v[130:133], v[212:215], v[14:17]
	v_mfma_f32_16x16x32_bf16 v[62:65], v[134:137], v[166:169], v[62:65]
	v_mfma_f32_16x16x32_bf16 v[58:61], v[142:145], v[166:169], v[58:61]
	v_mfma_f32_16x16x32_bf16 v[42:45], v[142:145], v[174:177], v[42:45]
	v_mfma_f32_16x16x32_bf16 v[46:49], v[134:137], v[174:177], v[46:49]
	v_mfma_f32_16x16x32_bf16 v[30:33], v[134:137], v[208:211], v[30:33]
	v_mfma_f32_16x16x32_bf16 v[26:29], v[142:145], v[208:211], v[26:29]
	v_mfma_f32_16x16x32_bf16 v[10:13], v[142:145], v[216:219], v[10:13]
	v_mfma_f32_16x16x32_bf16 v[14:17], v[134:137], v[216:219], v[14:17]
	s_setprio 0
	s_setprio 1
	v_mfma_f32_16x16x32_bf16 v[54:57], v[146:149], v[162:165], v[54:57]
	v_mfma_f32_16x16x32_bf16 v[50:53], v[154:157], v[162:165], v[50:53]
	v_mfma_f32_16x16x32_bf16 v[34:37], v[154:157], v[170:173], v[34:37]
	v_mfma_f32_16x16x32_bf16 v[38:41], v[146:149], v[170:173], v[38:41]
	v_mfma_f32_16x16x32_bf16 v[22:25], v[146:149], v[194:197], v[22:25]
	v_mfma_f32_16x16x32_bf16 v[18:21], v[154:157], v[194:197], v[18:21]
	v_mfma_f32_16x16x32_bf16 v[2:5], v[154:157], v[212:215], v[2:5]
	v_mfma_f32_16x16x32_bf16 v[6:9], v[146:149], v[212:215], v[6:9]
	v_mfma_f32_16x16x32_bf16 v[54:57], v[150:153], v[166:169], v[54:57]
	v_mfma_f32_16x16x32_bf16 v[50:53], v[158:161], v[166:169], v[50:53]
	v_mfma_f32_16x16x32_bf16 v[34:37], v[158:161], v[174:177], v[34:37]
	v_mfma_f32_16x16x32_bf16 v[38:41], v[150:153], v[174:177], v[38:41]
	v_mfma_f32_16x16x32_bf16 v[22:25], v[150:153], v[208:211], v[22:25]
	v_mfma_f32_16x16x32_bf16 v[18:21], v[158:161], v[208:211], v[18:21]
	v_mfma_f32_16x16x32_bf16 v[2:5], v[158:161], v[216:219], v[2:5]
	v_mfma_f32_16x16x32_bf16 v[6:9], v[150:153], v[216:219], v[6:9]
	s_setprio 0
	s_barrier
	s_add_i32 s75, 0, 0x18000
	s_add_i32 s76, 0, 0x1c000
	v_add_u32_e32 v142, s75, v201
	v_add_u32_e32 v158, s76, v201
	ds_read_b128 v[130:133], v142
	ds_read_b128 v[134:137], v142 offset:1024
	ds_read_b128 v[138:141], v142 offset:2048
	ds_read_b128 v[142:145], v142 offset:3072
	ds_read_b128 v[146:149], v158
	ds_read_b128 v[150:153], v158 offset:1024
	ds_read_b128 v[154:157], v158 offset:2048
	ds_read_b128 v[158:161], v158 offset:3072
	s_add_u32 s56, s56, 0x100000
	s_addc_u32 s57, s57, 0
	s_mov_b32 m0, s59
	v_lshl_add_u64 v[226:227], s[56:57], 0, v[178:179]
	ds_read_b128 v[162:165], v205 offset:32768
	ds_read_b128 v[166:169], v205 offset:33792
	ds_read_b128 v[170:173], v205 offset:34816
	ds_read_b128 v[174:177], v205 offset:35840
	ds_read_b128 v[194:197], v205 offset:36864
	ds_read_b128 v[208:211], v205 offset:37888
	ds_read_b128 v[212:215], v205 offset:38912
	ds_read_b128 v[216:219], v205 offset:39936
	global_load_lds_dwordx4 v[226:227], off
	v_lshl_add_u64 v[226:227], s[56:57], 0, v[182:183]
	s_mov_b32 m0, s60
	s_nop 0
	global_load_lds_dwordx4 v[226:227], off
	s_waitcnt vmcnt(8)
	s_waitcnt lgkmcnt(0)
	s_barrier
	s_setprio 1
	s_waitcnt lgkmcnt(0)
	v_mfma_f32_16x16x32_bf16 v[126:129], v[130:133], v[162:165], v[126:129]
	v_mfma_f32_16x16x32_bf16 v[122:125], v[138:141], v[162:165], v[122:125]
	v_mfma_f32_16x16x32_bf16 v[106:109], v[138:141], v[170:173], v[106:109]
	v_mfma_f32_16x16x32_bf16 v[110:113], v[130:133], v[170:173], v[110:113]
	v_mfma_f32_16x16x32_bf16 v[94:97], v[130:133], v[194:197], v[94:97]
	v_mfma_f32_16x16x32_bf16 v[90:93], v[138:141], v[194:197], v[90:93]
	v_mfma_f32_16x16x32_bf16 v[74:77], v[138:141], v[212:215], v[74:77]
	v_mfma_f32_16x16x32_bf16 v[78:81], v[130:133], v[212:215], v[78:81]
	v_mfma_f32_16x16x32_bf16 v[126:129], v[134:137], v[166:169], v[126:129]
	v_mfma_f32_16x16x32_bf16 v[122:125], v[142:145], v[166:169], v[122:125]
	v_mfma_f32_16x16x32_bf16 v[106:109], v[142:145], v[174:177], v[106:109]
	v_mfma_f32_16x16x32_bf16 v[110:113], v[134:137], v[174:177], v[110:113]
	v_mfma_f32_16x16x32_bf16 v[94:97], v[134:137], v[208:211], v[94:97]
	v_mfma_f32_16x16x32_bf16 v[90:93], v[142:145], v[208:211], v[90:93]
	v_mfma_f32_16x16x32_bf16 v[74:77], v[142:145], v[216:219], v[74:77]
	v_mfma_f32_16x16x32_bf16 v[78:81], v[134:137], v[216:219], v[78:81]
	s_setprio 0
	s_setprio 1
	v_mfma_f32_16x16x32_bf16 v[118:121], v[146:149], v[162:165], v[118:121]
	v_mfma_f32_16x16x32_bf16 v[114:117], v[154:157], v[162:165], v[114:117]
	v_mfma_f32_16x16x32_bf16 v[98:101], v[154:157], v[170:173], v[98:101]
	v_mfma_f32_16x16x32_bf16 v[102:105], v[146:149], v[170:173], v[102:105]
	v_mfma_f32_16x16x32_bf16 v[86:89], v[146:149], v[194:197], v[86:89]
	v_mfma_f32_16x16x32_bf16 v[82:85], v[154:157], v[194:197], v[82:85]
	v_mfma_f32_16x16x32_bf16 v[66:69], v[154:157], v[212:215], v[66:69]
	v_mfma_f32_16x16x32_bf16 v[70:73], v[146:149], v[212:215], v[70:73]
	v_mfma_f32_16x16x32_bf16 v[118:121], v[150:153], v[166:169], v[118:121]
	v_mfma_f32_16x16x32_bf16 v[114:117], v[158:161], v[166:169], v[114:117]
	v_mfma_f32_16x16x32_bf16 v[98:101], v[158:161], v[174:177], v[98:101]
	v_mfma_f32_16x16x32_bf16 v[102:105], v[150:153], v[174:177], v[102:105]
	v_mfma_f32_16x16x32_bf16 v[86:89], v[150:153], v[208:211], v[86:89]
	v_mfma_f32_16x16x32_bf16 v[82:85], v[158:161], v[208:211], v[82:85]
	v_mfma_f32_16x16x32_bf16 v[66:69], v[158:161], v[216:219], v[66:69]
	v_mfma_f32_16x16x32_bf16 v[70:73], v[150:153], v[216:219], v[70:73]
	s_setprio 0
	s_barrier
; #define PG8_STAGE(bufoff, gbase, voff) do { _Pragma("unroll") for (int _i = 0; _i < 2; ++_i) \
;         __builtin_amdgcn_global_load_lds((const unsigned*)((const char*)(gbase) + (voff)[_i]), (LAS unsigned*)(lds + (bufoff) + ldsw + _i * 8192), 16, 0, 0); } while (0)
; #define PG8_LDA(dst, b, h) do { _Pragma("unroll") for (int m = 0; m < 4; ++m) _Pragma("unroll") for (int k = 0; k < 2; ++k) dst[m][k] = *(const LAS bf16x8*)(lds + PG8_SA(b, h) + aoff + m * 2048 + k * 1024); } while (0)
; #define PG8_LDB(dst, b, h) do { _Pragma("unroll") for (int n = 0; n < 2; ++n) _Pragma("unroll") for (int k = 0; k < 2; ++k) dst[n][k] = *(const LAS bf16x8*)(lds + PG8_SB(b, h) + boff + n * 2048 + k * 1024); } while (0)
; template <class Epi, class Sched, bool ALIGN_EPI = true, bool SP2 = true>
; __device__ __forceinline__ void gemm_phase(LAS unsigned char* lds, const Gemm g, const Sched& S, const Epi& E) {
;     ...
;         for (int t = 0; t < nt; t += 2) {
;             const bool last = (t == nt - 2);
;             const char* a1 = cA + (size_t)(t + 1) * kstep;
;             const char* a2 = last ? nA : cA + (size_t)(t + 2) * kstep; const char* b2 = last ? nB : cB + (size_t)(t + 2) * kstep;
;             const char* a3 = a2 + kstep; const char* b3 = b2 + kstep;
;             if (last && has_next) S.a_ready(nxt);
;             if constexpr (SP2) {
;             PG8_LDB(B0, 0, 0); PG8_LDB(B1, 0, 1); PG8_SCHED; PG8_LDA(At, 0, 0); PG8_STAGE(PG8_SA(1, 1), a1 + hstep, voffA);
;             PG8_WAIT_V(8); PG8_WAIT_L(0); PG8_BAR; PG8_MMA(0, 0, At, B0); PG8_MMA(0, 1, At, B1); PG8_BAR; PG8_SCHED;
;             PG8_LDA(At, 0, 1); PG8_STAGE(PG8_SB(0, 0), b2, voffB); PG8_STAGE(PG8_SB(0, 1), b2 + hstep, voffB); PG8_STAGE(PG8_SA(0, 0), a2, voffA);
;             PG8_WAIT_V(8); PG8_WAIT_L(0); PG8_BAR; PG8_MMA(1, 0, At, B0); PG8_MMA(1, 1, At, B1); PG8_BAR; PG8_SCHED;
;             PG8_LDB(B0, 1, 0); PG8_LDB(B1, 1, 1); PG8_SCHED; PG8_LDA(At, 1, 0); PG8_STAGE(PG8_SA(0, 1), a2 + hstep, voffA);
;             PG8_WAIT_V(8); PG8_WAIT_L(0); PG8_BAR; PG8_MMA(0, 0, At, B0); PG8_MMA(0, 1, At, B1); PG8_BAR; PG8_SCHED;
;             PG8_LDA(At, 1, 1); PG8_STAGE(PG8_SB(1, 0), b3, voffB); PG8_STAGE(PG8_SB(1, 1), b3 + hstep, voffB); PG8_STAGE(PG8_SA(1, 0), a3, voffA);
;             PG8_WAIT_V(8); PG8_WAIT_L(0); PG8_BAR; PG8_MMA(1, 0, At, B0); PG8_MMA(1, 1, At, B1); PG8_BAR; PG8_SCHED;
	s_add_i32 s56, s75, s33
	v_lshl_add_u64 v[198:199], v[198:199], 0, s[22:23]
	s_mov_b32 m0, s56
	ds_read_b128 v[162:165], v205 offset:49152
	ds_read_b128 v[166:169], v205 offset:50176
	ds_read_b128 v[170:173], v205 offset:51200
	ds_read_b128 v[174:177], v205 offset:52224
	ds_read_b128 v[194:197], v205 offset:53248
	ds_read_b128 v[208:211], v205 offset:54272
	ds_read_b128 v[212:215], v205 offset:55296
	ds_read_b128 v[216:219], v205 offset:56320
	global_load_lds_dwordx4 v[198:199], off
	s_add_i32 m0, s56, 0x2000
	s_add_u32 s54, s54, 0x100080
	v_lshl_add_u64 v[198:199], v[220:221], 0, s[22:23]
	s_addc_u32 s55, s55, 0
	s_add_i32 s56, s76, s33
	global_load_lds_dwordx4 v[198:199], off
	v_lshl_add_u64 v[198:199], s[54:55], 0, v[180:181]
	s_mov_b32 m0, s56
	s_nop 0
	global_load_lds_dwordx4 v[198:199], off
	v_lshl_add_u64 v[198:199], s[54:55], 0, v[184:185]
	s_add_i32 m0, s56, 0x2000
	s_nop 0
	global_load_lds_dwordx4 v[198:199], off
	v_lshl_add_u64 v[198:199], v[222:223], 0, s[22:23]
	s_mov_b32 m0, s62
	s_nop 0
	global_load_lds_dwordx4 v[198:199], off
	v_lshl_add_u64 v[198:199], v[224:225], 0, s[22:23]
	s_mov_b32 m0, s63
	s_nop 0
	global_load_lds_dwordx4 v[198:199], off
	s_waitcnt vmcnt(8)
	s_waitcnt lgkmcnt(0)
	s_barrier
	s_setprio 1
	s_waitcnt lgkmcnt(0)
	v_mfma_f32_16x16x32_bf16 v[62:65], v[130:133], v[162:165], v[62:65]
	v_mfma_f32_16x16x32_bf16 v[58:61], v[138:141], v[162:165], v[58:61]
	v_mfma_f32_16x16x32_bf16 v[42:45], v[138:141], v[170:173], v[42:45]
	v_mfma_f32_16x16x32_bf16 v[46:49], v[130:133], v[170:173], v[46:49]
	v_mfma_f32_16x16x32_bf16 v[30:33], v[130:133], v[194:197], v[30:33]
	v_mfma_f32_16x16x32_bf16 v[26:29], v[138:141], v[194:197], v[26:29]
	v_mfma_f32_16x16x32_bf16 v[10:13], v[138:141], v[212:215], v[10:13]
	v_mfma_f32_16x16x32_bf16 v[14:17], v[130:133], v[212:215], v[14:17]
	v_mfma_f32_16x16x32_bf16 v[62:65], v[134:137], v[166:169], v[62:65]
	v_mfma_f32_16x16x32_bf16 v[58:61], v[142:145], v[166:169], v[58:61]
	v_mfma_f32_16x16x32_bf16 v[42:45], v[142:145], v[174:177], v[42:45]
	v_mfma_f32_16x16x32_bf16 v[46:49], v[134:137], v[174:177], v[46:49]
	v_mfma_f32_16x16x32_bf16 v[30:33], v[134:137], v[208:211], v[30:33]
	v_mfma_f32_16x16x32_bf16 v[26:29], v[142:145], v[208:211], v[26:29]
	v_mfma_f32_16x16x32_bf16 v[10:13], v[142:145], v[216:219], v[10:13]
	v_mfma_f32_16x16x32_bf16 v[14:17], v[134:137], v[216:219], v[14:17]
	s_setprio 0
	s_setprio 1
	v_mfma_f32_16x16x32_bf16 v[54:57], v[146:149], v[162:165], v[54:57]
	v_mfma_f32_16x16x32_bf16 v[50:53], v[154:157], v[162:165], v[50:53]
	v_mfma_f32_16x16x32_bf16 v[34:37], v[154:157], v[170:173], v[34:37]
	v_mfma_f32_16x16x32_bf16 v[38:41], v[146:149], v[170:173], v[38:41]
	v_mfma_f32_16x16x32_bf16 v[22:25], v[146:149], v[194:197], v[22:25]
	v_mfma_f32_16x16x32_bf16 v[18:21], v[154:157], v[194:197], v[18:21]
	v_mfma_f32_16x16x32_bf16 v[2:5], v[154:157], v[212:215], v[2:5]
	v_mfma_f32_16x16x32_bf16 v[6:9], v[146:149], v[212:215], v[6:9]
	v_mfma_f32_16x16x32_bf16 v[54:57], v[150:153], v[166:169], v[54:57]
	v_mfma_f32_16x16x32_bf16 v[50:53], v[158:161], v[166:169], v[50:53]
	v_mfma_f32_16x16x32_bf16 v[34:37], v[158:161], v[174:177], v[34:37]
	v_mfma_f32_16x16x32_bf16 v[38:41], v[150:153], v[174:177], v[38:41]
	v_mfma_f32_16x16x32_bf16 v[22:25], v[150:153], v[208:211], v[22:25]
	v_mfma_f32_16x16x32_bf16 v[18:21], v[158:161], v[208:211], v[18:21]
	v_mfma_f32_16x16x32_bf16 v[2:5], v[158:161], v[216:219], v[2:5]
	v_mfma_f32_16x16x32_bf16 v[6:9], v[150:153], v[216:219], v[6:9]
	s_setprio 0
	s_barrier
	s_add_i32 s74, s74, 2
	s_add_u32 s52, s52, 0x100
	s_addc_u32 s53, s53, 0
	s_add_u32 s72, s72, 0x100
	s_addc_u32 s73, s73, 0
	s_cmp_gt_u32 s74, 61
	s_cbranch_scc0 .LBB0_1639
	s_and_b64 vcc, exec, s[26:27]
	s_cbranch_vccz .LBB0_1642
	s_barrier

; #define PG8_STAGE(bufoff, gbase, voff) do { _Pragma("unroll") for (int _i = 0; _i < 2; ++_i) \
;         __builtin_amdgcn_global_load_lds((const unsigned*)((const char*)(gbase) + (voff)[_i]), (LAS unsigned*)(lds + (bufoff) + ldsw + _i * 8192), 16, 0, 0); } while (0)
; #define PG8_LDA(dst, b, h) do { _Pragma("unroll") for (int m = 0; m < 4; ++m) _Pragma("unroll") for (int k = 0; k < 2; ++k) dst[m][k] = *(const LAS bf16x8*)(lds + PG8_SA(b, h) + aoff + m * 2048 + k * 1024); } while (0)
; #define PG8_LDB(dst, b, h) do { _Pragma("unroll") for (int n = 0; n < 2; ++n) _Pragma("unroll") for (int k = 0; k < 2; ++k) dst[n][k] = *(const LAS bf16x8*)(lds + PG8_SB(b, h) + boff + n * 2048 + k * 1024); } while (0)
; #define PG8_MMA(ai, bj, At, Bt) do { __builtin_amdgcn_s_setprio(1); _Pragma("unroll") for (int m = 0; m < 4; ++m) _Pragma("unroll") for (int n = 0; n < 2; ++n) _Pragma("unroll") for (int k = 0; k < 2; ++k) \
;         acc[ai][bj][m][n] = __builtin_amdgcn_mfma_f32_16x16x32_bf16(Bt[n][k], At[m][k], acc[ai][bj][m][n], 0, 0, 0); __builtin_amdgcn_s_setprio(0); } while (0)
; #define PG8_WAIT_V(n) asm volatile("s_waitcnt vmcnt(" #n ")" ::: "memory")
; #define PG8_WAIT_L(n) asm volatile("s_waitcnt lgkmcnt(" #n ")" ::: "memory")
; #define PG8_BAR __builtin_amdgcn_s_barrier()
; #define PG8_SCHED __builtin_amdgcn_sched_barrier(0)
; template <class Epi, class Sched, bool ALIGN_EPI = true, bool SP2 = true>
; __device__ __forceinline__ void gemm_phase(LAS unsigned char* lds, const Gemm g, const Sched& S, const Epi& E) {
;     ...
;             const char* a1 = cA + (size_t)(t + 1) * kstep;
;             const char* a2 = last ? nA : cA + (size_t)(t + 2) * kstep; const char* b2 = last ? nB : cB + (size_t)(t + 2) * kstep;
;             const char* a3 = a2 + kstep; const char* b3 = b2 + kstep;
;             if (last && has_next) S.a_ready(nxt);
;             if constexpr (SP2) {
;             PG8_LDB(B0, 0, 0); PG8_LDB(B1, 0, 1); PG8_SCHED; PG8_LDA(At, 0, 0); PG8_STAGE(PG8_SA(1, 1), a1 + hstep, voffA);
;             PG8_WAIT_V(8); PG8_WAIT_L(0); PG8_BAR; PG8_MMA(0, 0, At, B0); PG8_MMA(0, 1, At, B1); PG8_BAR; PG8_SCHED;
;             PG8_LDA(At, 0, 1); PG8_STAGE(PG8_SB(0, 0), b2, voffB); PG8_STAGE(PG8_SB(0, 1), b2 + hstep, voffB); PG8_STAGE(PG8_SA(0, 0), a2, voffA);
;             PG8_WAIT_V(8); PG8_WAIT_L(0); PG8_BAR; PG8_MMA(1, 0, At, B0); PG8_MMA(1, 1, At, B1); PG8_BAR; PG8_SCHED;
.LBB0_2060:
	ds_read_b128 v[130:133], v187
	ds_read_b128 v[134:137], v187 offset:1024
	ds_read_b128 v[138:141], v187 offset:2048
	ds_read_b128 v[142:145], v187 offset:3072
	ds_read_b128 v[146:149], v188
	ds_read_b128 v[150:153], v188 offset:1024
	ds_read_b128 v[170:173], v188 offset:2048
	ds_read_b128 v[192:195], v188 offset:3072
	s_add_u32 s26, s24, 0xffd50080
	s_addc_u32 s27, s25, -1
	s_cmpk_eq_i32 s53, 0xa8
	s_cselect_b32 s29, s7, s27
	s_cselect_b32 s28, s6, s26
	s_cselect_b32 s27, s23, s52
	s_cselect_b32 s26, s22, s51
	v_lshl_add_u64 v[174:175], s[24:25], 0, v[162:163]
	s_add_i32 m0, s36, 0xc000
	ds_read_b128 v[196:199], v189
	ds_read_b128 v[200:203], v189 offset:1024
	ds_read_b128 v[204:207], v189 offset:2048
	ds_read_b128 v[208:211], v189 offset:3072
	ds_read_b128 v[212:215], v189 offset:4096
	ds_read_b128 v[216:219], v189 offset:5120
	ds_read_b128 v[220:223], v189 offset:6144
	ds_read_b128 v[224:227], v189 offset:7168
	global_load_lds_dwordx4 v[174:175], off
	v_lshl_add_u64 v[174:175], s[24:25], 0, v[164:165]
	s_add_i32 m0, s36, 0xe000
	s_nop 0
	global_load_lds_dwordx4 v[174:175], off
	s_waitcnt vmcnt(8)
	s_waitcnt lgkmcnt(0)
	s_barrier
	s_setprio 1
	s_waitcnt lgkmcnt(0)
	v_mfma_f32_16x16x32_bf16 v[126:129], v[130:133], v[196:199], v[126:129]
	v_mfma_f32_16x16x32_bf16 v[122:125], v[138:141], v[196:199], v[122:125]
	v_mfma_f32_16x16x32_bf16 v[106:109], v[138:141], v[204:207], v[106:109]
	v_mfma_f32_16x16x32_bf16 v[110:113], v[130:133], v[204:207], v[110:113]
	v_mfma_f32_16x16x32_bf16 v[94:97], v[130:133], v[212:215], v[94:97]
	v_mfma_f32_16x16x32_bf16 v[90:93], v[138:141], v[212:215], v[90:93]
	v_mfma_f32_16x16x32_bf16 v[74:77], v[138:141], v[220:223], v[74:77]
	v_mfma_f32_16x16x32_bf16 v[78:81], v[130:133], v[220:223], v[78:81]
	v_mfma_f32_16x16x32_bf16 v[126:129], v[134:137], v[200:203], v[126:129]
	v_mfma_f32_16x16x32_bf16 v[122:125], v[142:145], v[200:203], v[122:125]
	v_mfma_f32_16x16x32_bf16 v[106:109], v[142:145], v[208:211], v[106:109]
	v_mfma_f32_16x16x32_bf16 v[110:113], v[134:137], v[208:211], v[110:113]
	v_mfma_f32_16x16x32_bf16 v[94:97], v[134:137], v[216:219], v[94:97]
	v_mfma_f32_16x16x32_bf16 v[90:93], v[142:145], v[216:219], v[90:93]
	v_mfma_f32_16x16x32_bf16 v[74:77], v[142:145], v[224:227], v[74:77]
	v_mfma_f32_16x16x32_bf16 v[78:81], v[134:137], v[224:227], v[78:81]
	s_setprio 0
	s_setprio 1
	v_mfma_f32_16x16x32_bf16 v[118:121], v[146:149], v[196:199], v[118:121]
	v_mfma_f32_16x16x32_bf16 v[114:117], v[170:173], v[196:199], v[114:117]
	v_mfma_f32_16x16x32_bf16 v[98:101], v[170:173], v[204:207], v[98:101]
	v_mfma_f32_16x16x32_bf16 v[102:105], v[146:149], v[204:207], v[102:105]
	v_mfma_f32_16x16x32_bf16 v[86:89], v[146:149], v[212:215], v[86:89]
	v_mfma_f32_16x16x32_bf16 v[82:85], v[170:173], v[212:215], v[82:85]
	v_mfma_f32_16x16x32_bf16 v[66:69], v[170:173], v[220:223], v[66:69]
	v_mfma_f32_16x16x32_bf16 v[70:73], v[146:149], v[220:223], v[70:73]
	v_mfma_f32_16x16x32_bf16 v[118:121], v[150:153], v[200:203], v[118:121]
	v_mfma_f32_16x16x32_bf16 v[114:117], v[192:195], v[200:203], v[114:117]
	v_mfma_f32_16x16x32_bf16 v[98:101], v[192:195], v[208:211], v[98:101]
	v_mfma_f32_16x16x32_bf16 v[102:105], v[150:153], v[208:211], v[102:105]
	v_mfma_f32_16x16x32_bf16 v[86:89], v[150:153], v[216:219], v[86:89]
	v_mfma_f32_16x16x32_bf16 v[82:85], v[192:195], v[216:219], v[82:85]
	v_mfma_f32_16x16x32_bf16 v[66:69], v[192:195], v[224:227], v[66:69]
	v_mfma_f32_16x16x32_bf16 v[70:73], v[150:153], v[224:227], v[70:73]
	s_setprio 0
	s_barrier
	s_add_i32 s54, s45, s35
	v_lshl_add_u64 v[174:175], s[26:27], 0, v[156:157]
	s_mov_b32 m0, s54
	ds_read_b128 v[196:199], v189 offset:16384
	ds_read_b128 v[200:203], v189 offset:17408
	ds_read_b128 v[204:207], v189 offset:18432
	ds_read_b128 v[208:211], v189 offset:19456
	ds_read_b128 v[212:215], v189 offset:20480
	ds_read_b128 v[216:219], v189 offset:21504
	ds_read_b128 v[220:223], v189 offset:22528
	ds_read_b128 v[224:227], v189 offset:23552
	global_load_lds_dwordx4 v[174:175], off
	s_add_i32 m0, s54, 0x2000
	s_add_u32 s54, s26, 0x2b0000
	v_lshl_add_u64 v[228:229], s[26:27], 0, v[160:161]
	s_addc_u32 s55, s27, 0
	s_add_i32 s56, s46, s35
	global_load_lds_dwordx4 v[228:229], off
	v_lshl_add_u64 v[230:231], s[54:55], 0, v[156:157]
	s_mov_b32 m0, s56
	v_lshl_add_u64 v[232:233], s[28:29], 0, v[158:159]
	global_load_lds_dwordx4 v[230:231], off
	v_lshl_add_u64 v[230:231], s[54:55], 0, v[160:161]
	s_add_i32 m0, s56, 0x2000
	s_nop 0
	global_load_lds_dwordx4 v[230:231], off
	v_lshl_add_u64 v[230:231], s[28:29], 0, v[154:155]
	s_mov_b32 m0, s36
	s_nop 0
	global_load_lds_dwordx4 v[230:231], off
	s_mov_b32 m0, s37
	s_nop 0
	global_load_lds_dwordx4 v[232:233], off
	s_waitcnt vmcnt(8)
	s_waitcnt lgkmcnt(0)
	s_barrier
; #define PG8_STAGE(bufoff, gbase, voff) do { _Pragma("unroll") for (int _i = 0; _i < 2; ++_i) \
;         __builtin_amdgcn_global_load_lds((const unsigned*)((const char*)(gbase) + (voff)[_i]), (LAS unsigned*)(lds + (bufoff) + ldsw + _i * 8192), 16, 0, 0); } while (0)
; #define PG8_LDA(dst, b, h) do { _Pragma("unroll") for (int m = 0; m < 4; ++m) _Pragma("unroll") for (int k = 0; k < 2; ++k) dst[m][k] = *(const LAS bf16x8*)(lds + PG8_SA(b, h) + aoff + m * 2048 + k * 1024); } while (0)
; #define PG8_LDB(dst, b, h) do { _Pragma("unroll") for (int n = 0; n < 2; ++n) _Pragma("unroll") for (int k = 0; k < 2; ++k) dst[n][k] = *(const LAS bf16x8*)(lds + PG8_SB(b, h) + boff + n * 2048 + k * 1024); } while (0)
; #define PG8_MMA(ai, bj, At, Bt) do { __builtin_amdgcn_s_setprio(1); _Pragma("unroll") for (int m = 0; m < 4; ++m) _Pragma("unroll") for (int n = 0; n < 2; ++n) _Pragma("unroll") for (int k = 0; k < 2; ++k) \
;         acc[ai][bj][m][n] = __builtin_amdgcn_mfma_f32_16x16x32_bf16(Bt[n][k], At[m][k], acc[ai][bj][m][n], 0, 0, 0); __builtin_amdgcn_s_setprio(0); } while (0)
; #define PG8_WAIT_V(n) asm volatile("s_waitcnt vmcnt(" #n ")" ::: "memory")
; #define PG8_WAIT_L(n) asm volatile("s_waitcnt lgkmcnt(" #n ")" ::: "memory")
; #define PG8_BAR __builtin_amdgcn_s_barrier()
; #define PG8_SCHED __builtin_amdgcn_sched_barrier(0)
; template <class Epi, class Sched, bool ALIGN_EPI = true, bool SP2 = true>
; __device__ __forceinline__ void gemm_phase(LAS unsigned char* lds, const Gemm g, const Sched& S, const Epi& E) {
;     ...
;             PG8_WAIT_V(8); PG8_WAIT_L(0); PG8_BAR; PG8_MMA(1, 0, At, B0); PG8_MMA(1, 1, At, B1); PG8_BAR; PG8_SCHED;
;             PG8_LDB(B0, 1, 0); PG8_LDB(B1, 1, 1); PG8_SCHED; PG8_LDA(At, 1, 0); PG8_STAGE(PG8_SA(0, 1), a2 + hstep, voffA);
;             PG8_WAIT_V(8); PG8_WAIT_L(0); PG8_BAR; PG8_MMA(0, 0, At, B0); PG8_MMA(0, 1, At, B1); PG8_BAR; PG8_SCHED;
;             PG8_LDA(At, 1, 1); PG8_STAGE(PG8_SB(1, 0), b3, voffB); PG8_STAGE(PG8_SB(1, 1), b3 + hstep, voffB); PG8_STAGE(PG8_SA(1, 0), a3, voffA);
	s_setprio 1
	s_waitcnt lgkmcnt(0)
	v_mfma_f32_16x16x32_bf16 v[62:65], v[130:133], v[196:199], v[62:65]
	v_mfma_f32_16x16x32_bf16 v[58:61], v[138:141], v[196:199], v[58:61]
	v_mfma_f32_16x16x32_bf16 v[42:45], v[138:141], v[204:207], v[42:45]
	v_mfma_f32_16x16x32_bf16 v[46:49], v[130:133], v[204:207], v[46:49]
	v_mfma_f32_16x16x32_bf16 v[30:33], v[130:133], v[212:215], v[30:33]
	v_mfma_f32_16x16x32_bf16 v[26:29], v[138:141], v[212:215], v[26:29]
	v_mfma_f32_16x16x32_bf16 v[10:13], v[138:141], v[220:223], v[10:13]
	v_mfma_f32_16x16x32_bf16 v[14:17], v[130:133], v[220:223], v[14:17]
	v_mfma_f32_16x16x32_bf16 v[62:65], v[134:137], v[200:203], v[62:65]
	v_mfma_f32_16x16x32_bf16 v[58:61], v[142:145], v[200:203], v[58:61]
	v_mfma_f32_16x16x32_bf16 v[42:45], v[142:145], v[208:211], v[42:45]
	v_mfma_f32_16x16x32_bf16 v[46:49], v[134:137], v[208:211], v[46:49]
	v_mfma_f32_16x16x32_bf16 v[30:33], v[134:137], v[216:219], v[30:33]
	v_mfma_f32_16x16x32_bf16 v[26:29], v[142:145], v[216:219], v[26:29]
	v_mfma_f32_16x16x32_bf16 v[10:13], v[142:145], v[224:227], v[10:13]
	v_mfma_f32_16x16x32_bf16 v[14:17], v[134:137], v[224:227], v[14:17]
	s_setprio 0
	s_setprio 1
	v_mfma_f32_16x16x32_bf16 v[54:57], v[146:149], v[196:199], v[54:57]
	v_mfma_f32_16x16x32_bf16 v[50:53], v[170:173], v[196:199], v[50:53]
	v_mfma_f32_16x16x32_bf16 v[34:37], v[170:173], v[204:207], v[34:37]
	v_mfma_f32_16x16x32_bf16 v[38:41], v[146:149], v[204:207], v[38:41]
	v_mfma_f32_16x16x32_bf16 v[22:25], v[146:149], v[212:215], v[22:25]
	v_mfma_f32_16x16x32_bf16 v[18:21], v[170:173], v[212:215], v[18:21]
	v_mfma_f32_16x16x32_bf16 v[2:5], v[170:173], v[220:223], v[2:5]
	v_mfma_f32_16x16x32_bf16 v[6:9], v[146:149], v[220:223], v[6:9]
	v_mfma_f32_16x16x32_bf16 v[54:57], v[150:153], v[200:203], v[54:57]
	v_mfma_f32_16x16x32_bf16 v[50:53], v[192:195], v[200:203], v[50:53]
	v_mfma_f32_16x16x32_bf16 v[34:37], v[192:195], v[208:211], v[34:37]
	v_mfma_f32_16x16x32_bf16 v[38:41], v[150:153], v[208:211], v[38:41]
	v_mfma_f32_16x16x32_bf16 v[22:25], v[150:153], v[216:219], v[22:25]
	v_mfma_f32_16x16x32_bf16 v[18:21], v[192:195], v[216:219], v[18:21]
	v_mfma_f32_16x16x32_bf16 v[2:5], v[192:195], v[224:227], v[2:5]
	v_mfma_f32_16x16x32_bf16 v[6:9], v[150:153], v[224:227], v[6:9]
	s_setprio 0
	s_barrier
	s_add_i32 s54, 0, 0x18000
	s_add_i32 s55, 0, 0x1c000
	v_add_u32_e32 v142, s54, v185
	v_add_u32_e32 v191, s55, v185
	ds_read_b128 v[130:133], v142
	ds_read_b128 v[134:137], v142 offset:1024
	ds_read_b128 v[138:141], v142 offset:2048
	ds_read_b128 v[142:145], v142 offset:3072
	ds_read_b128 v[146:149], v191
	ds_read_b128 v[150:153], v191 offset:1024
	ds_read_b128 v[170:173], v191 offset:2048
	ds_read_b128 v[192:195], v191 offset:3072
	s_add_u32 s28, s28, 0x2b0000
	s_addc_u32 s29, s29, 0
	s_mov_b32 m0, s38
	v_lshl_add_u64 v[234:235], s[28:29], 0, v[154:155]
	ds_read_b128 v[196:199], v189 offset:32768
	ds_read_b128 v[200:203], v189 offset:33792
	ds_read_b128 v[204:207], v189 offset:34816
	ds_read_b128 v[208:211], v189 offset:35840
	ds_read_b128 v[212:215], v189 offset:36864
	ds_read_b128 v[216:219], v189 offset:37888
	ds_read_b128 v[220:223], v189 offset:38912
	ds_read_b128 v[224:227], v189 offset:39936
	global_load_lds_dwordx4 v[234:235], off
	v_lshl_add_u64 v[234:235], s[28:29], 0, v[158:159]
	s_mov_b32 m0, s39
	s_nop 0
	global_load_lds_dwordx4 v[234:235], off
	s_waitcnt vmcnt(8)
	s_waitcnt lgkmcnt(0)
	s_barrier
	s_setprio 1
	s_waitcnt lgkmcnt(0)
	v_mfma_f32_16x16x32_bf16 v[126:129], v[130:133], v[196:199], v[126:129]
	v_mfma_f32_16x16x32_bf16 v[122:125], v[138:141], v[196:199], v[122:125]
	v_mfma_f32_16x16x32_bf16 v[106:109], v[138:141], v[204:207], v[106:109]
	v_mfma_f32_16x16x32_bf16 v[110:113], v[130:133], v[204:207], v[110:113]
	v_mfma_f32_16x16x32_bf16 v[94:97], v[130:133], v[212:215], v[94:97]
	v_mfma_f32_16x16x32_bf16 v[90:93], v[138:141], v[212:215], v[90:93]
	v_mfma_f32_16x16x32_bf16 v[74:77], v[138:141], v[220:223], v[74:77]
	v_mfma_f32_16x16x32_bf16 v[78:81], v[130:133], v[220:223], v[78:81]
	v_mfma_f32_16x16x32_bf16 v[126:129], v[134:137], v[200:203], v[126:129]
	v_mfma_f32_16x16x32_bf16 v[122:125], v[142:145], v[200:203], v[122:125]
	v_mfma_f32_16x16x32_bf16 v[106:109], v[142:145], v[208:211], v[106:109]
	v_mfma_f32_16x16x32_bf16 v[110:113], v[134:137], v[208:211], v[110:113]
	v_mfma_f32_16x16x32_bf16 v[94:97], v[134:137], v[216:219], v[94:97]
	v_mfma_f32_16x16x32_bf16 v[90:93], v[142:145], v[216:219], v[90:93]
	v_mfma_f32_16x16x32_bf16 v[74:77], v[142:145], v[224:227], v[74:77]
	v_mfma_f32_16x16x32_bf16 v[78:81], v[134:137], v[224:227], v[78:81]
	s_setprio 0
	s_setprio 1
	v_mfma_f32_16x16x32_bf16 v[118:121], v[146:149], v[196:199], v[118:121]
	v_mfma_f32_16x16x32_bf16 v[114:117], v[170:173], v[196:199], v[114:117]
	v_mfma_f32_16x16x32_bf16 v[98:101], v[170:173], v[204:207], v[98:101]
	v_mfma_f32_16x16x32_bf16 v[102:105], v[146:149], v[204:207], v[102:105]
	v_mfma_f32_16x16x32_bf16 v[86:89], v[146:149], v[212:215], v[86:89]
	v_mfma_f32_16x16x32_bf16 v[82:85], v[170:173], v[212:215], v[82:85]
	v_mfma_f32_16x16x32_bf16 v[66:69], v[170:173], v[220:223], v[66:69]
	v_mfma_f32_16x16x32_bf16 v[70:73], v[146:149], v[220:223], v[70:73]
	v_mfma_f32_16x16x32_bf16 v[118:121], v[150:153], v[200:203], v[118:121]
	v_mfma_f32_16x16x32_bf16 v[114:117], v[192:195], v[200:203], v[114:117]
	v_mfma_f32_16x16x32_bf16 v[98:101], v[192:195], v[208:211], v[98:101]
	v_mfma_f32_16x16x32_bf16 v[102:105], v[150:153], v[208:211], v[102:105]
	v_mfma_f32_16x16x32_bf16 v[86:89], v[150:153], v[216:219], v[86:89]
	v_mfma_f32_16x16x32_bf16 v[82:85], v[192:195], v[216:219], v[82:85]
	v_mfma_f32_16x16x32_bf16 v[66:69], v[192:195], v[224:227], v[66:69]
	v_mfma_f32_16x16x32_bf16 v[70:73], v[150:153], v[224:227], v[70:73]
	s_setprio 0
	s_barrier
; #define PG8_STAGE(bufoff, gbase, voff) do { _Pragma("unroll") for (int _i = 0; _i < 2; ++_i) \
;         __builtin_amdgcn_global_load_lds((const unsigned*)((const char*)(gbase) + (voff)[_i]), (LAS unsigned*)(lds + (bufoff) + ldsw + _i * 8192), 16, 0, 0); } while (0)
; #define PG8_LDA(dst, b, h) do { _Pragma("unroll") for (int m = 0; m < 4; ++m) _Pragma("unroll") for (int k = 0; k < 2; ++k) dst[m][k] = *(const LAS bf16x8*)(lds + PG8_SA(b, h) + aoff + m * 2048 + k * 1024); } while (0)
; #define PG8_MMA(ai, bj, At, Bt) do { __builtin_amdgcn_s_setprio(1); _Pragma("unroll") for (int m = 0; m < 4; ++m) _Pragma("unroll") for (int n = 0; n < 2; ++n) _Pragma("unroll") for (int k = 0; k < 2; ++k) \
;         acc[ai][bj][m][n] = __builtin_amdgcn_mfma_f32_16x16x32_bf16(Bt[n][k], At[m][k], acc[ai][bj][m][n], 0, 0, 0); __builtin_amdgcn_s_setprio(0); } while (0)
; #define PG8_WAIT_V(n) asm volatile("s_waitcnt vmcnt(" #n ")" ::: "memory")
; #define PG8_WAIT_L(n) asm volatile("s_waitcnt lgkmcnt(" #n ")" ::: "memory")
; #define PG8_BAR __builtin_amdgcn_s_barrier()
; #define PG8_SCHED __builtin_amdgcn_sched_barrier(0)
; template <class Epi, class Sched, bool ALIGN_EPI = true, bool SP2 = true>
; __device__ __forceinline__ void gemm_phase(LAS unsigned char* lds, const Gemm g, const Sched& S, const Epi& E) {
;     ...
;             PG8_LDA(At, 1, 1); PG8_STAGE(PG8_SB(1, 0), b3, voffB); PG8_STAGE(PG8_SB(1, 1), b3 + hstep, voffB); PG8_STAGE(PG8_SA(1, 0), a3, voffA);
;             PG8_WAIT_V(8); PG8_WAIT_L(0); PG8_BAR; PG8_MMA(1, 0, At, B0); PG8_MMA(1, 1, At, B1); PG8_BAR; PG8_SCHED;
;     ...
;         if constexpr (ALIGN_EPI) { if (wr == 0) PG8_BAR; }
	s_add_i32 s28, s54, s35
	v_lshl_add_u64 v[174:175], v[174:175], 0, s[18:19]
	s_mov_b32 m0, s28
	ds_read_b128 v[196:199], v189 offset:49152
	ds_read_b128 v[200:203], v189 offset:50176
	ds_read_b128 v[204:207], v189 offset:51200
	ds_read_b128 v[208:211], v189 offset:52224
	ds_read_b128 v[212:215], v189 offset:53248
	ds_read_b128 v[216:219], v189 offset:54272
	ds_read_b128 v[220:223], v189 offset:55296
	ds_read_b128 v[224:227], v189 offset:56320
	global_load_lds_dwordx4 v[174:175], off
	s_add_i32 m0, s28, 0x2000
	s_add_u32 s26, s26, 0x2b0080
	v_lshl_add_u64 v[174:175], v[228:229], 0, s[18:19]
	s_addc_u32 s27, s27, 0
	s_add_i32 s28, s55, s35
	global_load_lds_dwordx4 v[174:175], off
	v_lshl_add_u64 v[174:175], s[26:27], 0, v[156:157]
	s_mov_b32 m0, s28
	s_nop 0
	global_load_lds_dwordx4 v[174:175], off
	v_lshl_add_u64 v[174:175], s[26:27], 0, v[160:161]
	s_add_i32 m0, s28, 0x2000
	s_nop 0
	global_load_lds_dwordx4 v[174:175], off
	v_lshl_add_u64 v[174:175], v[230:231], 0, s[18:19]
	s_mov_b32 m0, s41
	s_nop 0
	global_load_lds_dwordx4 v[174:175], off
	v_lshl_add_u64 v[174:175], v[232:233], 0, s[18:19]
	s_mov_b32 m0, s42
	s_nop 0
	global_load_lds_dwordx4 v[174:175], off
	s_waitcnt vmcnt(8)
	s_waitcnt lgkmcnt(0)
	s_barrier
	s_setprio 1
	s_waitcnt lgkmcnt(0)
	v_mfma_f32_16x16x32_bf16 v[62:65], v[130:133], v[196:199], v[62:65]
	v_mfma_f32_16x16x32_bf16 v[58:61], v[138:141], v[196:199], v[58:61]
	v_mfma_f32_16x16x32_bf16 v[42:45], v[138:141], v[204:207], v[42:45]
	v_mfma_f32_16x16x32_bf16 v[46:49], v[130:133], v[204:207], v[46:49]
	v_mfma_f32_16x16x32_bf16 v[30:33], v[130:133], v[212:215], v[30:33]
	v_mfma_f32_16x16x32_bf16 v[26:29], v[138:141], v[212:215], v[26:29]
	v_mfma_f32_16x16x32_bf16 v[10:13], v[138:141], v[220:223], v[10:13]
	v_mfma_f32_16x16x32_bf16 v[14:17], v[130:133], v[220:223], v[14:17]
	v_mfma_f32_16x16x32_bf16 v[62:65], v[134:137], v[200:203], v[62:65]
	v_mfma_f32_16x16x32_bf16 v[58:61], v[142:145], v[200:203], v[58:61]
	v_mfma_f32_16x16x32_bf16 v[42:45], v[142:145], v[208:211], v[42:45]
	v_mfma_f32_16x16x32_bf16 v[46:49], v[134:137], v[208:211], v[46:49]
	v_mfma_f32_16x16x32_bf16 v[30:33], v[134:137], v[216:219], v[30:33]
	v_mfma_f32_16x16x32_bf16 v[26:29], v[142:145], v[216:219], v[26:29]
	v_mfma_f32_16x16x32_bf16 v[10:13], v[142:145], v[224:227], v[10:13]
	v_mfma_f32_16x16x32_bf16 v[14:17], v[134:137], v[224:227], v[14:17]
	s_setprio 0
	s_setprio 1
	v_mfma_f32_16x16x32_bf16 v[54:57], v[146:149], v[196:199], v[54:57]
	v_mfma_f32_16x16x32_bf16 v[50:53], v[170:173], v[196:199], v[50:53]
	v_mfma_f32_16x16x32_bf16 v[34:37], v[170:173], v[204:207], v[34:37]
	v_mfma_f32_16x16x32_bf16 v[38:41], v[146:149], v[204:207], v[38:41]
	v_mfma_f32_16x16x32_bf16 v[22:25], v[146:149], v[212:215], v[22:25]
	v_mfma_f32_16x16x32_bf16 v[18:21], v[170:173], v[212:215], v[18:21]
	v_mfma_f32_16x16x32_bf16 v[2:5], v[170:173], v[220:223], v[2:5]
	v_mfma_f32_16x16x32_bf16 v[6:9], v[146:149], v[220:223], v[6:9]
	v_mfma_f32_16x16x32_bf16 v[54:57], v[150:153], v[200:203], v[54:57]
	v_mfma_f32_16x16x32_bf16 v[50:53], v[192:195], v[200:203], v[50:53]
	v_mfma_f32_16x16x32_bf16 v[34:37], v[192:195], v[208:211], v[34:37]
	v_mfma_f32_16x16x32_bf16 v[38:41], v[150:153], v[208:211], v[38:41]
	v_mfma_f32_16x16x32_bf16 v[22:25], v[150:153], v[216:219], v[22:25]
	v_mfma_f32_16x16x32_bf16 v[18:21], v[192:195], v[216:219], v[18:21]
	v_mfma_f32_16x16x32_bf16 v[2:5], v[192:195], v[224:227], v[2:5]
	v_mfma_f32_16x16x32_bf16 v[6:9], v[150:153], v[224:227], v[6:9]
	s_setprio 0
	s_barrier
	s_add_i32 s53, s53, 2
	s_add_u32 s24, s24, 0x100
	s_addc_u32 s25, s25, 0
	s_add_u32 s51, s51, 0x100
	s_addc_u32 s52, s52, 0
	s_cmpk_gt_u32 s53, 0xa9
	s_cbranch_scc0 .LBB0_2060
	s_and_b64 vcc, exec, s[20:21]
	s_cbranch_vccz .LBB0_2063
	s_barrier

;     __host__ __device__ bool next(int i, Unit& u) const { const bool ok = StaticOrder::next(i >> 1, u); u.z = i & 1; return ok; }
; #define PG8_STAGE(bufoff, gbase, voff) do { _Pragma("unroll") for (int _i = 0; _i < 2; ++_i) \
;         __builtin_amdgcn_global_load_lds((const unsigned*)((const char*)(gbase) + (voff)[_i]), (LAS unsigned*)(lds + (bufoff) + ldsw + _i * 8192), 16, 0, 0); } while (0)
; #define PG8_LDA(dst, b, h) do { _Pragma("unroll") for (int m = 0; m < 4; ++m) _Pragma("unroll") for (int k = 0; k < 2; ++k) dst[m][k] = *(const LAS bf16x8*)(lds + PG8_SA(b, h) + aoff + m * 2048 + k * 1024); } while (0)
; #define PG8_LDB(dst, b, h) do { _Pragma("unroll") for (int n = 0; n < 2; ++n) _Pragma("unroll") for (int k = 0; k < 2; ++k) dst[n][k] = *(const LAS bf16x8*)(lds + PG8_SB(b, h) + boff + n * 2048 + k * 1024); } while (0)
; #define PG8_WAIT_V(n) asm volatile("s_waitcnt vmcnt(" #n ")" ::: "memory")
; #define PG8_WAIT_L(n) asm volatile("s_waitcnt lgkmcnt(" #n ")" ::: "memory")
; #define PG8_BAR __builtin_amdgcn_s_barrier()
; template <class Epi, class Sched, bool ALIGN_EPI = true, bool SP2 = true>
; __device__ __forceinline__ void gemm_phase(LAS unsigned char* lds, const Gemm g, const Sched& S, const Epi& E) {
;     ...
;         const bool has_next = S.next(ui + 1, nxt);
;         const char* nA = has_next ? PG8_ABASE(nxt) : cA; const char* nB = has_next ? PG8_BBASE(nxt) : cB;
;         for (int t = 0; t < nt; t += 2) {
;             const bool last = (t == nt - 2);
;             const char* a1 = cA + (size_t)(t + 1) * kstep;
;             const char* a2 = last ? nA : cA + (size_t)(t + 2) * kstep; const char* b2 = last ? nB : cB + (size_t)(t + 2) * kstep;
;             const char* a3 = a2 + kstep; const char* b3 = b2 + kstep;
;             if (last && has_next) S.a_ready(nxt);
;             if constexpr (SP2) {
;             PG8_LDB(B0, 0, 0); PG8_LDB(B1, 0, 1); PG8_SCHED; PG8_LDA(At, 0, 0); PG8_STAGE(PG8_SA(1, 1), a1 + hstep, voffA);
;             PG8_WAIT_V(8); PG8_WAIT_L(0); PG8_BAR; PG8_MMA(0, 0, At, B0); PG8_MMA(0, 1, At, B1); PG8_BAR; PG8_SCHED;
;             PG8_LDA(At, 0, 1); PG8_STAGE(PG8_SB(0, 0), b2, voffB); PG8_STAGE(PG8_SB(0, 1), b2 + hstep, voffB); PG8_STAGE(PG8_SA(0, 0), a2, voffA);
;             PG8_WAIT_V(8); PG8_WAIT_L(0); PG8_BAR; PG8_MMA(1, 0, At, B0); PG8_MMA(1, 1, At, B1); PG8_BAR; PG8_SCHED;
.LBB0_2100:
	s_add_u32 s31, s24, s30
	s_addc_u32 s38, s25, 0
	s_add_u32 s36, s31, 0x100
	s_addc_u32 s37, s38, 0
	s_and_b64 s[34:35], s[28:29], exec
	s_cselect_b32 s35, s15, s37
	s_cselect_b32 s34, s57, s36
	s_add_u32 s30, s22, s30
	s_addc_u32 s36, s23, 0
	s_add_u32 s30, s30, 0x100
	s_addc_u32 s36, s36, 0
	s_and_b64 s[28:29], s[28:29], exec
	s_cselect_b32 s37, s13, s36
	s_cselect_b32 s36, s58, s30
	s_add_u32 s40, s31, 0x10080
	ds_read_b128 v[142:145], v148
	ds_read_b128 v[152:155], v148 offset:1024
	ds_read_b128 v[156:159], v148 offset:2048
	ds_read_b128 v[160:163], v148 offset:3072
	ds_read_b128 v[164:167], v149
	ds_read_b128 v[168:171], v149 offset:1024
	ds_read_b128 v[172:175], v149 offset:2048
	ds_read_b128 v[176:179], v149 offset:3072
	s_addc_u32 s41, s38, 0
	s_add_i32 s66, s54, s46
	s_add_i32 m0, s21, 0xc000
	s_add_i32 s69, s21, 0xe000
	s_add_i32 s63, s66, 0x2000
	s_add_u32 s38, s36, 0x10000
	s_addc_u32 s39, s37, 0
	s_add_i32 s65, s55, s46
	s_add_i32 s64, s65, 0x2000
	s_add_i32 s62, 0, 0x18000
	s_add_i32 s61, 0, 0x1c000
	s_add_u32 s30, s34, 0x10000
	s_addc_u32 s31, s35, 0
	s_add_i32 s60, s62, s46
	s_add_i32 s59, s60, 0x2000
	s_add_u32 s28, s36, 0x10080
	s_addc_u32 s29, s37, 0
	s_add_i32 s68, s61, s46
	s_add_i32 s67, s68, 0x2000
	v_lshl_add_u64 v[212:213], s[40:41], 0, v[130:131]
	ds_read_b128 v[180:183], v150
	ds_read_b128 v[184:187], v150 offset:1024
	ds_read_b128 v[188:191], v150 offset:2048
	ds_read_b128 v[192:195], v150 offset:3072
	ds_read_b128 v[196:199], v150 offset:4096
	ds_read_b128 v[200:203], v150 offset:5120
	ds_read_b128 v[204:207], v150 offset:6144
	ds_read_b128 v[208:211], v150 offset:7168
	global_load_lds_dwordx4 v[212:213], off
	v_lshl_add_u64 v[212:213], s[40:41], 0, v[134:135]
	s_mov_b32 m0, s69
	s_nop 0
	global_load_lds_dwordx4 v[212:213], off
	s_waitcnt vmcnt(8)
	s_waitcnt lgkmcnt(0)
	s_barrier
	s_setprio 1
	s_waitcnt lgkmcnt(0)
	v_mfma_f32_16x16x32_bf16 v[126:129], v[142:145], v[180:183], v[126:129]
	v_mfma_f32_16x16x32_bf16 v[122:125], v[156:159], v[180:183], v[122:125]
	v_mfma_f32_16x16x32_bf16 v[110:113], v[156:159], v[188:191], v[110:113]
	v_mfma_f32_16x16x32_bf16 v[118:121], v[142:145], v[188:191], v[118:121]
	v_mfma_f32_16x16x32_bf16 v[102:105], v[142:145], v[196:199], v[102:105]
	v_mfma_f32_16x16x32_bf16 v[94:97], v[156:159], v[196:199], v[94:97]
	v_mfma_f32_16x16x32_bf16 v[78:81], v[156:159], v[204:207], v[78:81]
	v_mfma_f32_16x16x32_bf16 v[86:89], v[142:145], v[204:207], v[86:89]
	v_mfma_f32_16x16x32_bf16 v[126:129], v[152:155], v[184:187], v[126:129]
	v_mfma_f32_16x16x32_bf16 v[122:125], v[160:163], v[184:187], v[122:125]
	v_mfma_f32_16x16x32_bf16 v[110:113], v[160:163], v[192:195], v[110:113]
	v_mfma_f32_16x16x32_bf16 v[118:121], v[152:155], v[192:195], v[118:121]
	v_mfma_f32_16x16x32_bf16 v[102:105], v[152:155], v[200:203], v[102:105]
	v_mfma_f32_16x16x32_bf16 v[94:97], v[160:163], v[200:203], v[94:97]
	v_mfma_f32_16x16x32_bf16 v[78:81], v[160:163], v[208:211], v[78:81]
	v_mfma_f32_16x16x32_bf16 v[86:89], v[152:155], v[208:211], v[86:89]
	s_setprio 0
	s_setprio 1
	v_mfma_f32_16x16x32_bf16 v[114:117], v[164:167], v[180:183], v[114:117]
	v_mfma_f32_16x16x32_bf16 v[106:109], v[172:175], v[180:183], v[106:109]
	v_mfma_f32_16x16x32_bf16 v[90:93], v[172:175], v[188:191], v[90:93]
	v_mfma_f32_16x16x32_bf16 v[98:101], v[164:167], v[188:191], v[98:101]
	v_mfma_f32_16x16x32_bf16 v[82:85], v[164:167], v[196:199], v[82:85]
	v_mfma_f32_16x16x32_bf16 v[74:77], v[172:175], v[196:199], v[74:77]
	v_mfma_f32_16x16x32_bf16 v[66:69], v[172:175], v[204:207], v[66:69]
	v_mfma_f32_16x16x32_bf16 v[70:73], v[164:167], v[204:207], v[70:73]
	v_mfma_f32_16x16x32_bf16 v[114:117], v[168:171], v[184:187], v[114:117]
	v_mfma_f32_16x16x32_bf16 v[106:109], v[176:179], v[184:187], v[106:109]
	v_mfma_f32_16x16x32_bf16 v[90:93], v[176:179], v[192:195], v[90:93]
	v_mfma_f32_16x16x32_bf16 v[98:101], v[168:171], v[192:195], v[98:101]
	v_mfma_f32_16x16x32_bf16 v[82:85], v[168:171], v[200:203], v[82:85]
	v_mfma_f32_16x16x32_bf16 v[74:77], v[176:179], v[200:203], v[74:77]
	v_mfma_f32_16x16x32_bf16 v[66:69], v[176:179], v[208:211], v[66:69]
	v_mfma_f32_16x16x32_bf16 v[70:73], v[168:171], v[208:211], v[70:73]
	s_setprio 0
	s_barrier
	s_mov_b32 m0, s66
	v_lshl_add_u64 v[212:213], s[36:37], 0, v[132:133]
	ds_read_b128 v[180:183], v150 offset:16384
	ds_read_b128 v[184:187], v150 offset:17408
	ds_read_b128 v[188:191], v150 offset:18432
	ds_read_b128 v[192:195], v150 offset:19456
	ds_read_b128 v[196:199], v150 offset:20480
	ds_read_b128 v[200:203], v150 offset:21504
	ds_read_b128 v[204:207], v150 offset:22528
	ds_read_b128 v[208:211], v150 offset:23552
	global_load_lds_dwordx4 v[212:213], off
	v_lshl_add_u64 v[214:215], s[36:37], 0, v[136:137]
	s_mov_b32 m0, s63
	v_lshl_add_u64 v[216:217], s[38:39], 0, v[132:133]
	global_load_lds_dwordx4 v[214:215], off
	s_mov_b32 m0, s65
	v_lshl_add_u64 v[218:219], s[34:35], 0, v[134:135]
	global_load_lds_dwordx4 v[216:217], off
	v_lshl_add_u64 v[216:217], s[38:39], 0, v[136:137]
	s_mov_b32 m0, s64
	s_nop 0
	global_load_lds_dwordx4 v[216:217], off
	v_lshl_add_u64 v[216:217], s[34:35], 0, v[130:131]
	s_mov_b32 m0, s21
	s_nop 0
	global_load_lds_dwordx4 v[216:217], off
	s_mov_b32 m0, s47
	s_nop 0
	global_load_lds_dwordx4 v[218:219], off
	s_waitcnt vmcnt(8)
	s_waitcnt lgkmcnt(0)
	s_barrier
; #define PG8_STAGE(bufoff, gbase, voff) do { _Pragma("unroll") for (int _i = 0; _i < 2; ++_i) \
;         __builtin_amdgcn_global_load_lds((const unsigned*)((const char*)(gbase) + (voff)[_i]), (LAS unsigned*)(lds + (bufoff) + ldsw + _i * 8192), 16, 0, 0); } while (0)
; #define PG8_LDA(dst, b, h) do { _Pragma("unroll") for (int m = 0; m < 4; ++m) _Pragma("unroll") for (int k = 0; k < 2; ++k) dst[m][k] = *(const LAS bf16x8*)(lds + PG8_SA(b, h) + aoff + m * 2048 + k * 1024); } while (0)
; #define PG8_LDB(dst, b, h) do { _Pragma("unroll") for (int n = 0; n < 2; ++n) _Pragma("unroll") for (int k = 0; k < 2; ++k) dst[n][k] = *(const LAS bf16x8*)(lds + PG8_SB(b, h) + boff + n * 2048 + k * 1024); } while (0)
; #define PG8_MMA(ai, bj, At, Bt) do { __builtin_amdgcn_s_setprio(1); _Pragma("unroll") for (int m = 0; m < 4; ++m) _Pragma("unroll") for (int n = 0; n < 2; ++n) _Pragma("unroll") for (int k = 0; k < 2; ++k) \
;         acc[ai][bj][m][n] = __builtin_amdgcn_mfma_f32_16x16x32_bf16(Bt[n][k], At[m][k], acc[ai][bj][m][n], 0, 0, 0); __builtin_amdgcn_s_setprio(0); } while (0)
; #define PG8_WAIT_V(n) asm volatile("s_waitcnt vmcnt(" #n ")" ::: "memory")
; #define PG8_WAIT_L(n) asm volatile("s_waitcnt lgkmcnt(" #n ")" ::: "memory")
; #define PG8_BAR __builtin_amdgcn_s_barrier()
; #define PG8_SCHED __builtin_amdgcn_sched_barrier(0)
; template <class Epi, class Sched, bool ALIGN_EPI = true, bool SP2 = true>
; __device__ __forceinline__ void gemm_phase(LAS unsigned char* lds, const Gemm g, const Sched& S, const Epi& E) {
;     ...
;             PG8_WAIT_V(8); PG8_WAIT_L(0); PG8_BAR; PG8_MMA(1, 0, At, B0); PG8_MMA(1, 1, At, B1); PG8_BAR; PG8_SCHED;
;             PG8_LDB(B0, 1, 0); PG8_LDB(B1, 1, 1); PG8_SCHED; PG8_LDA(At, 1, 0); PG8_STAGE(PG8_SA(0, 1), a2 + hstep, voffA);
;             PG8_WAIT_V(8); PG8_WAIT_L(0); PG8_BAR; PG8_MMA(0, 0, At, B0); PG8_MMA(0, 1, At, B1); PG8_BAR; PG8_SCHED;
	s_setprio 1
	s_waitcnt lgkmcnt(0)
	v_mfma_f32_16x16x32_bf16 v[62:65], v[142:145], v[180:183], v[62:65]
	v_mfma_f32_16x16x32_bf16 v[58:61], v[156:159], v[180:183], v[58:61]
	v_mfma_f32_16x16x32_bf16 v[46:49], v[156:159], v[188:191], v[46:49]
	v_mfma_f32_16x16x32_bf16 v[54:57], v[142:145], v[188:191], v[54:57]
	v_mfma_f32_16x16x32_bf16 v[38:41], v[142:145], v[196:199], v[38:41]
	v_mfma_f32_16x16x32_bf16 v[30:33], v[156:159], v[196:199], v[30:33]
	v_mfma_f32_16x16x32_bf16 v[14:17], v[156:159], v[204:207], v[14:17]
	v_mfma_f32_16x16x32_bf16 v[22:25], v[142:145], v[204:207], v[22:25]
	v_mfma_f32_16x16x32_bf16 v[62:65], v[152:155], v[184:187], v[62:65]
	v_mfma_f32_16x16x32_bf16 v[58:61], v[160:163], v[184:187], v[58:61]
	v_mfma_f32_16x16x32_bf16 v[46:49], v[160:163], v[192:195], v[46:49]
	v_mfma_f32_16x16x32_bf16 v[54:57], v[152:155], v[192:195], v[54:57]
	v_mfma_f32_16x16x32_bf16 v[38:41], v[152:155], v[200:203], v[38:41]
	v_mfma_f32_16x16x32_bf16 v[30:33], v[160:163], v[200:203], v[30:33]
	v_mfma_f32_16x16x32_bf16 v[14:17], v[160:163], v[208:211], v[14:17]
	v_mfma_f32_16x16x32_bf16 v[22:25], v[152:155], v[208:211], v[22:25]
	s_setprio 0
	s_setprio 1
	v_mfma_f32_16x16x32_bf16 v[50:53], v[164:167], v[180:183], v[50:53]
	v_mfma_f32_16x16x32_bf16 v[42:45], v[172:175], v[180:183], v[42:45]
	v_mfma_f32_16x16x32_bf16 v[26:29], v[172:175], v[188:191], v[26:29]
	v_mfma_f32_16x16x32_bf16 v[34:37], v[164:167], v[188:191], v[34:37]
	v_mfma_f32_16x16x32_bf16 v[18:21], v[164:167], v[196:199], v[18:21]
	v_mfma_f32_16x16x32_bf16 v[10:13], v[172:175], v[196:199], v[10:13]
	v_mfma_f32_16x16x32_bf16 v[2:5], v[172:175], v[204:207], v[2:5]
	v_mfma_f32_16x16x32_bf16 v[6:9], v[164:167], v[204:207], v[6:9]
	v_mfma_f32_16x16x32_bf16 v[50:53], v[168:171], v[184:187], v[50:53]
	v_mfma_f32_16x16x32_bf16 v[42:45], v[176:179], v[184:187], v[42:45]
	v_mfma_f32_16x16x32_bf16 v[26:29], v[176:179], v[192:195], v[26:29]
	v_mfma_f32_16x16x32_bf16 v[34:37], v[168:171], v[192:195], v[34:37]
	v_mfma_f32_16x16x32_bf16 v[18:21], v[168:171], v[200:203], v[18:21]
	v_mfma_f32_16x16x32_bf16 v[10:13], v[176:179], v[200:203], v[10:13]
	v_mfma_f32_16x16x32_bf16 v[2:5], v[176:179], v[208:211], v[2:5]
	v_mfma_f32_16x16x32_bf16 v[6:9], v[168:171], v[208:211], v[6:9]
	s_setprio 0
	s_barrier
	v_add_u32_e32 v151, s62, v147
	ds_read_b128 v[142:145], v151
	ds_read_b128 v[152:155], v151 offset:1024
	ds_read_b128 v[156:159], v151 offset:2048
	ds_read_b128 v[160:163], v151 offset:3072
	v_add_u32_e32 v151, s61, v147
	ds_read_b128 v[164:167], v151
	ds_read_b128 v[168:171], v151 offset:1024
	ds_read_b128 v[172:175], v151 offset:2048
	ds_read_b128 v[176:179], v151 offset:3072
	s_mov_b32 m0, s48
	v_lshl_add_u64 v[220:221], s[30:31], 0, v[130:131]
	ds_read_b128 v[180:183], v150 offset:32768
	ds_read_b128 v[184:187], v150 offset:33792
	ds_read_b128 v[188:191], v150 offset:34816
	ds_read_b128 v[192:195], v150 offset:35840
	ds_read_b128 v[196:199], v150 offset:36864
	ds_read_b128 v[200:203], v150 offset:37888
	ds_read_b128 v[204:207], v150 offset:38912
	ds_read_b128 v[208:211], v150 offset:39936
	global_load_lds_dwordx4 v[220:221], off
	v_lshl_add_u64 v[220:221], s[30:31], 0, v[134:135]
	s_mov_b32 m0, s49
	s_nop 0
	global_load_lds_dwordx4 v[220:221], off
	s_waitcnt vmcnt(8)
	s_waitcnt lgkmcnt(0)
	s_barrier
	s_setprio 1
	s_waitcnt lgkmcnt(0)
	v_mfma_f32_16x16x32_bf16 v[126:129], v[142:145], v[180:183], v[126:129]
	v_mfma_f32_16x16x32_bf16 v[122:125], v[156:159], v[180:183], v[122:125]
	v_mfma_f32_16x16x32_bf16 v[110:113], v[156:159], v[188:191], v[110:113]
	v_mfma_f32_16x16x32_bf16 v[118:121], v[142:145], v[188:191], v[118:121]
	v_mfma_f32_16x16x32_bf16 v[102:105], v[142:145], v[196:199], v[102:105]
	v_mfma_f32_16x16x32_bf16 v[94:97], v[156:159], v[196:199], v[94:97]
	v_mfma_f32_16x16x32_bf16 v[78:81], v[156:159], v[204:207], v[78:81]
	v_mfma_f32_16x16x32_bf16 v[86:89], v[142:145], v[204:207], v[86:89]
	v_mfma_f32_16x16x32_bf16 v[126:129], v[152:155], v[184:187], v[126:129]
	v_mfma_f32_16x16x32_bf16 v[122:125], v[160:163], v[184:187], v[122:125]
	v_mfma_f32_16x16x32_bf16 v[110:113], v[160:163], v[192:195], v[110:113]
	v_mfma_f32_16x16x32_bf16 v[118:121], v[152:155], v[192:195], v[118:121]
	v_mfma_f32_16x16x32_bf16 v[102:105], v[152:155], v[200:203], v[102:105]
	v_mfma_f32_16x16x32_bf16 v[94:97], v[160:163], v[200:203], v[94:97]
	v_mfma_f32_16x16x32_bf16 v[78:81], v[160:163], v[208:211], v[78:81]
	v_mfma_f32_16x16x32_bf16 v[86:89], v[152:155], v[208:211], v[86:89]
	s_setprio 0
	s_setprio 1
	v_mfma_f32_16x16x32_bf16 v[114:117], v[164:167], v[180:183], v[114:117]
	v_mfma_f32_16x16x32_bf16 v[106:109], v[172:175], v[180:183], v[106:109]
	v_mfma_f32_16x16x32_bf16 v[90:93], v[172:175], v[188:191], v[90:93]
	v_mfma_f32_16x16x32_bf16 v[98:101], v[164:167], v[188:191], v[98:101]
	v_mfma_f32_16x16x32_bf16 v[82:85], v[164:167], v[196:199], v[82:85]
	v_mfma_f32_16x16x32_bf16 v[74:77], v[172:175], v[196:199], v[74:77]
	v_mfma_f32_16x16x32_bf16 v[66:69], v[172:175], v[204:207], v[66:69]
	v_mfma_f32_16x16x32_bf16 v[70:73], v[164:167], v[204:207], v[70:73]
	v_mfma_f32_16x16x32_bf16 v[114:117], v[168:171], v[184:187], v[114:117]
	v_mfma_f32_16x16x32_bf16 v[106:109], v[176:179], v[184:187], v[106:109]
	v_mfma_f32_16x16x32_bf16 v[90:93], v[176:179], v[192:195], v[90:93]
	v_mfma_f32_16x16x32_bf16 v[98:101], v[168:171], v[192:195], v[98:101]
	v_mfma_f32_16x16x32_bf16 v[82:85], v[168:171], v[200:203], v[82:85]
	v_mfma_f32_16x16x32_bf16 v[74:77], v[176:179], v[200:203], v[74:77]
	v_mfma_f32_16x16x32_bf16 v[66:69], v[176:179], v[208:211], v[66:69]
	v_mfma_f32_16x16x32_bf16 v[70:73], v[168:171], v[208:211], v[70:73]
	s_setprio 0
	s_barrier
; #define PG8_STAGE(bufoff, gbase, voff) do { _Pragma("unroll") for (int _i = 0; _i < 2; ++_i) \
;         __builtin_amdgcn_global_load_lds((const unsigned*)((const char*)(gbase) + (voff)[_i]), (LAS unsigned*)(lds + (bufoff) + ldsw + _i * 8192), 16, 0, 0); } while (0)
; #define PG8_LDA(dst, b, h) do { _Pragma("unroll") for (int m = 0; m < 4; ++m) _Pragma("unroll") for (int k = 0; k < 2; ++k) dst[m][k] = *(const LAS bf16x8*)(lds + PG8_SA(b, h) + aoff + m * 2048 + k * 1024); } while (0)
; #define PG8_MMA(ai, bj, At, Bt) do { __builtin_amdgcn_s_setprio(1); _Pragma("unroll") for (int m = 0; m < 4; ++m) _Pragma("unroll") for (int n = 0; n < 2; ++n) _Pragma("unroll") for (int k = 0; k < 2; ++k) \
;         acc[ai][bj][m][n] = __builtin_amdgcn_mfma_f32_16x16x32_bf16(Bt[n][k], At[m][k], acc[ai][bj][m][n], 0, 0, 0); __builtin_amdgcn_s_setprio(0); } while (0)
; #define PG8_WAIT_V(n) asm volatile("s_waitcnt vmcnt(" #n ")" ::: "memory")
; #define PG8_WAIT_L(n) asm volatile("s_waitcnt lgkmcnt(" #n ")" ::: "memory")
; #define PG8_BAR __builtin_amdgcn_s_barrier()
; #define PG8_SCHED __builtin_amdgcn_sched_barrier(0)
; template <class Epi, class Sched, bool ALIGN_EPI = true, bool SP2 = true>
; __device__ __forceinline__ void gemm_phase(LAS unsigned char* lds, const Gemm g, const Sched& S, const Epi& E) {
;     ...
;             PG8_LDA(At, 1, 1); PG8_STAGE(PG8_SB(1, 0), b3, voffB); PG8_STAGE(PG8_SB(1, 1), b3 + hstep, voffB); PG8_STAGE(PG8_SA(1, 0), a3, voffA);
;             PG8_WAIT_V(8); PG8_WAIT_L(0); PG8_BAR; PG8_MMA(1, 0, At, B0); PG8_MMA(1, 1, At, B1); PG8_BAR; PG8_SCHED;
;     ...
;         if constexpr (ALIGN_EPI) { if (wr == 0) PG8_BAR; }
	s_mov_b32 m0, s60
	v_lshl_add_u64 v[212:213], v[212:213], 0, s[6:7]
	ds_read_b128 v[180:183], v150 offset:49152
	ds_read_b128 v[184:187], v150 offset:50176
	ds_read_b128 v[188:191], v150 offset:51200
	ds_read_b128 v[192:195], v150 offset:52224
	ds_read_b128 v[196:199], v150 offset:53248
	ds_read_b128 v[200:203], v150 offset:54272
	ds_read_b128 v[204:207], v150 offset:55296
	ds_read_b128 v[208:211], v150 offset:56320
	global_load_lds_dwordx4 v[212:213], off
	v_lshl_add_u64 v[212:213], v[214:215], 0, s[6:7]
	s_mov_b32 m0, s59
	s_nop 0
	global_load_lds_dwordx4 v[212:213], off
	v_lshl_add_u64 v[212:213], s[28:29], 0, v[132:133]
	s_mov_b32 m0, s68
	s_nop 0
	global_load_lds_dwordx4 v[212:213], off
	v_lshl_add_u64 v[212:213], s[28:29], 0, v[136:137]
	s_mov_b32 m0, s67
	s_nop 0
	global_load_lds_dwordx4 v[212:213], off
	v_lshl_add_u64 v[212:213], v[216:217], 0, s[6:7]
	s_mov_b32 m0, s51
	s_nop 0
	global_load_lds_dwordx4 v[212:213], off
	v_lshl_add_u64 v[212:213], v[218:219], 0, s[6:7]
	s_mov_b32 m0, s52
	s_nop 0
	global_load_lds_dwordx4 v[212:213], off
	s_waitcnt vmcnt(8)
	s_waitcnt lgkmcnt(0)
	s_barrier
	s_setprio 1
	s_waitcnt lgkmcnt(0)
	v_mfma_f32_16x16x32_bf16 v[62:65], v[142:145], v[180:183], v[62:65]
	v_mfma_f32_16x16x32_bf16 v[58:61], v[156:159], v[180:183], v[58:61]
	v_mfma_f32_16x16x32_bf16 v[46:49], v[156:159], v[188:191], v[46:49]
	v_mfma_f32_16x16x32_bf16 v[54:57], v[142:145], v[188:191], v[54:57]
	v_mfma_f32_16x16x32_bf16 v[38:41], v[142:145], v[196:199], v[38:41]
	v_mfma_f32_16x16x32_bf16 v[30:33], v[156:159], v[196:199], v[30:33]
	v_mfma_f32_16x16x32_bf16 v[14:17], v[156:159], v[204:207], v[14:17]
	v_mfma_f32_16x16x32_bf16 v[22:25], v[142:145], v[204:207], v[22:25]
	v_mfma_f32_16x16x32_bf16 v[62:65], v[152:155], v[184:187], v[62:65]
	v_mfma_f32_16x16x32_bf16 v[58:61], v[160:163], v[184:187], v[58:61]
	v_mfma_f32_16x16x32_bf16 v[46:49], v[160:163], v[192:195], v[46:49]
	v_mfma_f32_16x16x32_bf16 v[54:57], v[152:155], v[192:195], v[54:57]
	v_mfma_f32_16x16x32_bf16 v[38:41], v[152:155], v[200:203], v[38:41]
	v_mfma_f32_16x16x32_bf16 v[30:33], v[160:163], v[200:203], v[30:33]
	v_mfma_f32_16x16x32_bf16 v[14:17], v[160:163], v[208:211], v[14:17]
	v_mfma_f32_16x16x32_bf16 v[22:25], v[152:155], v[208:211], v[22:25]
	s_setprio 0
	s_setprio 1
	v_mfma_f32_16x16x32_bf16 v[50:53], v[164:167], v[180:183], v[50:53]
	v_mfma_f32_16x16x32_bf16 v[42:45], v[172:175], v[180:183], v[42:45]
	v_mfma_f32_16x16x32_bf16 v[26:29], v[172:175], v[188:191], v[26:29]
	v_mfma_f32_16x16x32_bf16 v[34:37], v[164:167], v[188:191], v[34:37]
	v_mfma_f32_16x16x32_bf16 v[18:21], v[164:167], v[196:199], v[18:21]
	v_mfma_f32_16x16x32_bf16 v[10:13], v[172:175], v[196:199], v[10:13]
	v_mfma_f32_16x16x32_bf16 v[2:5], v[172:175], v[204:207], v[2:5]
	v_mfma_f32_16x16x32_bf16 v[6:9], v[164:167], v[204:207], v[6:9]
	v_mfma_f32_16x16x32_bf16 v[50:53], v[168:171], v[184:187], v[50:53]
	v_mfma_f32_16x16x32_bf16 v[42:45], v[176:179], v[184:187], v[42:45]
	v_mfma_f32_16x16x32_bf16 v[26:29], v[176:179], v[192:195], v[26:29]
	v_mfma_f32_16x16x32_bf16 v[34:37], v[168:171], v[192:195], v[34:37]
	v_mfma_f32_16x16x32_bf16 v[18:21], v[168:171], v[200:203], v[18:21]
	v_mfma_f32_16x16x32_bf16 v[10:13], v[176:179], v[200:203], v[10:13]
	v_mfma_f32_16x16x32_bf16 v[2:5], v[176:179], v[208:211], v[2:5]
	v_mfma_f32_16x16x32_bf16 v[6:9], v[168:171], v[208:211], v[6:9]
	s_setprio 0
	s_barrier
	s_movk_i32 s30, 0x100
	s_andn2_b64 vcc, exec, s[26:27]
	s_mov_b64 s[28:29], -1
	s_mov_b64 s[26:27], 0
	s_cbranch_vccz .LBB0_2100
	s_and_b64 vcc, exec, s[10:11]
	s_cbranch_vccz .LBB0_2103
	s_barrier

; #define PG8_STAGE(bufoff, gbase, voff) do { _Pragma("unroll") for (int _i = 0; _i < 2; ++_i) \
;         __builtin_amdgcn_global_load_lds((const unsigned*)((const char*)(gbase) + (voff)[_i]), (LAS unsigned*)(lds + (bufoff) + ldsw + _i * 8192), 16, 0, 0); } while (0)
; #define PG8_LDA(dst, b, h) do { _Pragma("unroll") for (int m = 0; m < 4; ++m) _Pragma("unroll") for (int k = 0; k < 2; ++k) dst[m][k] = *(const LAS bf16x8*)(lds + PG8_SA(b, h) + aoff + m * 2048 + k * 1024); } while (0)
; #define PG8_LDB(dst, b, h) do { _Pragma("unroll") for (int n = 0; n < 2; ++n) _Pragma("unroll") for (int k = 0; k < 2; ++k) dst[n][k] = *(const LAS bf16x8*)(lds + PG8_SB(b, h) + boff + n * 2048 + k * 1024); } while (0)
; #define PG8_MMA(ai, bj, At, Bt) do { __builtin_amdgcn_s_setprio(1); _Pragma("unroll") for (int m = 0; m < 4; ++m) _Pragma("unroll") for (int n = 0; n < 2; ++n) _Pragma("unroll") for (int k = 0; k < 2; ++k) \
;         acc[ai][bj][m][n] = __builtin_amdgcn_mfma_f32_16x16x32_bf16(Bt[n][k], At[m][k], acc[ai][bj][m][n], 0, 0, 0); __builtin_amdgcn_s_setprio(0); } while (0)
; #define PG8_WAIT_V(n) asm volatile("s_waitcnt vmcnt(" #n ")" ::: "memory")
; #define PG8_WAIT_L(n) asm volatile("s_waitcnt lgkmcnt(" #n ")" ::: "memory")
; #define PG8_BAR __builtin_amdgcn_s_barrier()
; #define PG8_SCHED __builtin_amdgcn_sched_barrier(0)
; template <class Epi, class Sched, bool ALIGN_EPI = true, bool SP2 = true>
; __device__ __forceinline__ void gemm_phase(LAS unsigned char* lds, const Gemm g, const Sched& S, const Epi& E) {
;     ...
;             const char* a1 = cA + (size_t)(t + 1) * kstep;
;             const char* a2 = last ? nA : cA + (size_t)(t + 2) * kstep; const char* b2 = last ? nB : cB + (size_t)(t + 2) * kstep;
;             const char* a3 = a2 + kstep; const char* b3 = b2 + kstep;
;             if (last && has_next) S.a_ready(nxt);
;             if constexpr (SP2) {
;             PG8_LDB(B0, 0, 0); PG8_LDB(B1, 0, 1); PG8_SCHED; PG8_LDA(At, 0, 0); PG8_STAGE(PG8_SA(1, 1), a1 + hstep, voffA);
;             PG8_WAIT_V(8); PG8_WAIT_L(0); PG8_BAR; PG8_MMA(0, 0, At, B0); PG8_MMA(0, 1, At, B1); PG8_BAR; PG8_SCHED;
;             PG8_LDA(At, 0, 1); PG8_STAGE(PG8_SB(0, 0), b2, voffB); PG8_STAGE(PG8_SB(0, 1), b2 + hstep, voffB); PG8_STAGE(PG8_SA(0, 0), a2, voffA);
;             PG8_WAIT_V(8); PG8_WAIT_L(0); PG8_BAR; PG8_MMA(1, 0, At, B0); PG8_MMA(1, 1, At, B1); PG8_BAR; PG8_SCHED;
.LBB0_2179:
	ds_read_b128 v[120:123], v201
	ds_read_b128 v[124:127], v201 offset:1024
	ds_read_b128 v[132:135], v201 offset:2048
	ds_read_b128 v[140:143], v201 offset:3072
	ds_read_b128 v[144:147], v202
	ds_read_b128 v[148:151], v202 offset:1024
	ds_read_b128 v[152:155], v202 offset:2048
	ds_read_b128 v[156:159], v202 offset:3072
	s_add_u32 s36, s34, 0xfff00080
	s_addc_u32 s37, s35, -1
	s_cmp_eq_u32 s61, 60
	s_cselect_b32 s39, s27, s37
	s_cselect_b32 s38, s57, s36
	s_cselect_b32 s37, s25, s60
	s_cselect_b32 s36, s58, s59
	v_lshl_add_u64 v[196:197], s[34:35], 0, v[184:185]
	s_add_i32 m0, s43, 0xc000
	ds_read_b128 v[160:163], v203
	ds_read_b128 v[164:167], v203 offset:1024
	ds_read_b128 v[168:171], v203 offset:2048
	ds_read_b128 v[172:175], v203 offset:3072
	ds_read_b128 v[192:195], v203 offset:4096
	ds_read_b128 v[206:209], v203 offset:5120
	ds_read_b128 v[210:213], v203 offset:6144
	ds_read_b128 v[214:217], v203 offset:7168
	global_load_lds_dwordx4 v[196:197], off
	v_lshl_add_u64 v[196:197], s[34:35], 0, v[186:187]
	s_add_i32 m0, s43, 0xe000
	s_nop 0
	global_load_lds_dwordx4 v[196:197], off
	s_waitcnt vmcnt(8)
	s_waitcnt lgkmcnt(0)
	s_barrier
	s_setprio 1
	s_waitcnt lgkmcnt(0)
	v_mfma_f32_16x16x32_bf16 v[136:139], v[120:123], v[160:163], v[136:139]
	v_mfma_f32_16x16x32_bf16 v[128:131], v[132:135], v[160:163], v[128:131]
	v_mfma_f32_16x16x32_bf16 v[104:107], v[132:135], v[168:171], v[104:107]
	v_mfma_f32_16x16x32_bf16 v[108:111], v[120:123], v[168:171], v[108:111]
	v_mfma_f32_16x16x32_bf16 v[92:95], v[120:123], v[192:195], v[92:95]
	v_mfma_f32_16x16x32_bf16 v[88:91], v[132:135], v[192:195], v[88:91]
	v_mfma_f32_16x16x32_bf16 v[72:75], v[132:135], v[210:213], v[72:75]
	v_mfma_f32_16x16x32_bf16 v[76:79], v[120:123], v[210:213], v[76:79]
	v_mfma_f32_16x16x32_bf16 v[136:139], v[124:127], v[164:167], v[136:139]
	v_mfma_f32_16x16x32_bf16 v[128:131], v[140:143], v[164:167], v[128:131]
	v_mfma_f32_16x16x32_bf16 v[104:107], v[140:143], v[172:175], v[104:107]
	v_mfma_f32_16x16x32_bf16 v[108:111], v[124:127], v[172:175], v[108:111]
	v_mfma_f32_16x16x32_bf16 v[92:95], v[124:127], v[206:209], v[92:95]
	v_mfma_f32_16x16x32_bf16 v[88:91], v[140:143], v[206:209], v[88:91]
	v_mfma_f32_16x16x32_bf16 v[72:75], v[140:143], v[214:217], v[72:75]
	v_mfma_f32_16x16x32_bf16 v[76:79], v[124:127], v[214:217], v[76:79]
	s_setprio 0
	s_setprio 1
	v_mfma_f32_16x16x32_bf16 v[116:119], v[144:147], v[160:163], v[116:119]
	v_mfma_f32_16x16x32_bf16 v[112:115], v[152:155], v[160:163], v[112:115]
	v_mfma_f32_16x16x32_bf16 v[96:99], v[152:155], v[168:171], v[96:99]
	v_mfma_f32_16x16x32_bf16 v[100:103], v[144:147], v[168:171], v[100:103]
	v_mfma_f32_16x16x32_bf16 v[84:87], v[144:147], v[192:195], v[84:87]
	v_mfma_f32_16x16x32_bf16 v[80:83], v[152:155], v[192:195], v[80:83]
	v_mfma_f32_16x16x32_bf16 v[64:67], v[152:155], v[210:213], v[64:67]
	v_mfma_f32_16x16x32_bf16 v[68:71], v[144:147], v[210:213], v[68:71]
	v_mfma_f32_16x16x32_bf16 v[116:119], v[148:151], v[164:167], v[116:119]
	v_mfma_f32_16x16x32_bf16 v[112:115], v[156:159], v[164:167], v[112:115]
	v_mfma_f32_16x16x32_bf16 v[96:99], v[156:159], v[172:175], v[96:99]
	v_mfma_f32_16x16x32_bf16 v[100:103], v[148:151], v[172:175], v[100:103]
	v_mfma_f32_16x16x32_bf16 v[84:87], v[148:151], v[206:209], v[84:87]
	v_mfma_f32_16x16x32_bf16 v[80:83], v[156:159], v[206:209], v[80:83]
	v_mfma_f32_16x16x32_bf16 v[64:67], v[156:159], v[214:217], v[64:67]
	v_mfma_f32_16x16x32_bf16 v[68:71], v[148:151], v[214:217], v[68:71]
	s_setprio 0
	s_barrier
	s_add_i32 s62, s51, s42
	v_lshl_add_u64 v[196:197], s[36:37], 0, v[178:179]
	s_mov_b32 m0, s62
	ds_read_b128 v[160:163], v203 offset:16384
	ds_read_b128 v[164:167], v203 offset:17408
	ds_read_b128 v[168:171], v203 offset:18432
	ds_read_b128 v[172:175], v203 offset:19456
	ds_read_b128 v[192:195], v203 offset:20480
	ds_read_b128 v[206:209], v203 offset:21504
	ds_read_b128 v[210:213], v203 offset:22528
	ds_read_b128 v[214:217], v203 offset:23552
	global_load_lds_dwordx4 v[196:197], off
	s_add_i32 m0, s62, 0x2000
	s_add_u32 s62, s36, 0x100000
	v_lshl_add_u64 v[218:219], s[36:37], 0, v[182:183]
	s_addc_u32 s63, s37, 0
	s_add_i32 s64, s52, s42
	global_load_lds_dwordx4 v[218:219], off
	v_lshl_add_u64 v[220:221], s[62:63], 0, v[178:179]
	s_mov_b32 m0, s64
	v_lshl_add_u64 v[222:223], s[38:39], 0, v[180:181]
	global_load_lds_dwordx4 v[220:221], off
	v_lshl_add_u64 v[220:221], s[62:63], 0, v[182:183]
	s_add_i32 m0, s64, 0x2000
	s_nop 0
	global_load_lds_dwordx4 v[220:221], off
	v_lshl_add_u64 v[220:221], s[38:39], 0, v[176:177]
	s_mov_b32 m0, s43
	s_nop 0
	global_load_lds_dwordx4 v[220:221], off
	s_mov_b32 m0, s44
	s_nop 0
	global_load_lds_dwordx4 v[222:223], off
	s_waitcnt vmcnt(8)
	s_waitcnt lgkmcnt(0)
	s_barrier
; #define PG8_STAGE(bufoff, gbase, voff) do { _Pragma("unroll") for (int _i = 0; _i < 2; ++_i) \
;         __builtin_amdgcn_global_load_lds((const unsigned*)((const char*)(gbase) + (voff)[_i]), (LAS unsigned*)(lds + (bufoff) + ldsw + _i * 8192), 16, 0, 0); } while (0)
; #define PG8_LDA(dst, b, h) do { _Pragma("unroll") for (int m = 0; m < 4; ++m) _Pragma("unroll") for (int k = 0; k < 2; ++k) dst[m][k] = *(const LAS bf16x8*)(lds + PG8_SA(b, h) + aoff + m * 2048 + k * 1024); } while (0)
; #define PG8_LDB(dst, b, h) do { _Pragma("unroll") for (int n = 0; n < 2; ++n) _Pragma("unroll") for (int k = 0; k < 2; ++k) dst[n][k] = *(const LAS bf16x8*)(lds + PG8_SB(b, h) + boff + n * 2048 + k * 1024); } while (0)
; #define PG8_MMA(ai, bj, At, Bt) do { __builtin_amdgcn_s_setprio(1); _Pragma("unroll") for (int m = 0; m < 4; ++m) _Pragma("unroll") for (int n = 0; n < 2; ++n) _Pragma("unroll") for (int k = 0; k < 2; ++k) \
;         acc[ai][bj][m][n] = __builtin_amdgcn_mfma_f32_16x16x32_bf16(Bt[n][k], At[m][k], acc[ai][bj][m][n], 0, 0, 0); __builtin_amdgcn_s_setprio(0); } while (0)
; #define PG8_WAIT_V(n) asm volatile("s_waitcnt vmcnt(" #n ")" ::: "memory")
; #define PG8_WAIT_L(n) asm volatile("s_waitcnt lgkmcnt(" #n ")" ::: "memory")
; #define PG8_BAR __builtin_amdgcn_s_barrier()
; #define PG8_SCHED __builtin_amdgcn_sched_barrier(0)
; template <class Epi, class Sched, bool ALIGN_EPI = true, bool SP2 = true>
; __device__ __forceinline__ void gemm_phase(LAS unsigned char* lds, const Gemm g, const Sched& S, const Epi& E) {
;     ...
;             PG8_WAIT_V(8); PG8_WAIT_L(0); PG8_BAR; PG8_MMA(1, 0, At, B0); PG8_MMA(1, 1, At, B1); PG8_BAR; PG8_SCHED;
;             PG8_LDB(B0, 1, 0); PG8_LDB(B1, 1, 1); PG8_SCHED; PG8_LDA(At, 1, 0); PG8_STAGE(PG8_SA(0, 1), a2 + hstep, voffA);
;             PG8_WAIT_V(8); PG8_WAIT_L(0); PG8_BAR; PG8_MMA(0, 0, At, B0); PG8_MMA(0, 1, At, B1); PG8_BAR; PG8_SCHED;
;             PG8_LDA(At, 1, 1); PG8_STAGE(PG8_SB(1, 0), b3, voffB); PG8_STAGE(PG8_SB(1, 1), b3 + hstep, voffB); PG8_STAGE(PG8_SA(1, 0), a3, voffA);
	s_setprio 1
	s_waitcnt lgkmcnt(0)
	v_mfma_f32_16x16x32_bf16 v[60:63], v[120:123], v[160:163], v[60:63]
	v_mfma_f32_16x16x32_bf16 v[56:59], v[132:135], v[160:163], v[56:59]
	v_mfma_f32_16x16x32_bf16 v[40:43], v[132:135], v[168:171], v[40:43]
	v_mfma_f32_16x16x32_bf16 v[44:47], v[120:123], v[168:171], v[44:47]
	v_mfma_f32_16x16x32_bf16 v[28:31], v[120:123], v[192:195], v[28:31]
	v_mfma_f32_16x16x32_bf16 v[24:27], v[132:135], v[192:195], v[24:27]
	v_mfma_f32_16x16x32_bf16 v[8:11], v[132:135], v[210:213], v[8:11]
	v_mfma_f32_16x16x32_bf16 v[12:15], v[120:123], v[210:213], v[12:15]
	v_mfma_f32_16x16x32_bf16 v[60:63], v[124:127], v[164:167], v[60:63]
	v_mfma_f32_16x16x32_bf16 v[56:59], v[140:143], v[164:167], v[56:59]
	v_mfma_f32_16x16x32_bf16 v[40:43], v[140:143], v[172:175], v[40:43]
	v_mfma_f32_16x16x32_bf16 v[44:47], v[124:127], v[172:175], v[44:47]
	v_mfma_f32_16x16x32_bf16 v[28:31], v[124:127], v[206:209], v[28:31]
	v_mfma_f32_16x16x32_bf16 v[24:27], v[140:143], v[206:209], v[24:27]
	v_mfma_f32_16x16x32_bf16 v[8:11], v[140:143], v[214:217], v[8:11]
	v_mfma_f32_16x16x32_bf16 v[12:15], v[124:127], v[214:217], v[12:15]
	s_setprio 0
	s_setprio 1
	v_mfma_f32_16x16x32_bf16 v[52:55], v[144:147], v[160:163], v[52:55]
	v_mfma_f32_16x16x32_bf16 v[48:51], v[152:155], v[160:163], v[48:51]
	v_mfma_f32_16x16x32_bf16 v[32:35], v[152:155], v[168:171], v[32:35]
	v_mfma_f32_16x16x32_bf16 v[36:39], v[144:147], v[168:171], v[36:39]
	v_mfma_f32_16x16x32_bf16 v[20:23], v[144:147], v[192:195], v[20:23]
	v_mfma_f32_16x16x32_bf16 v[16:19], v[152:155], v[192:195], v[16:19]
	v_mfma_f32_16x16x32_bf16 v[0:3], v[152:155], v[210:213], v[0:3]
	v_mfma_f32_16x16x32_bf16 v[4:7], v[144:147], v[210:213], v[4:7]
	v_mfma_f32_16x16x32_bf16 v[52:55], v[148:151], v[164:167], v[52:55]
	v_mfma_f32_16x16x32_bf16 v[48:51], v[156:159], v[164:167], v[48:51]
	v_mfma_f32_16x16x32_bf16 v[32:35], v[156:159], v[172:175], v[32:35]
	v_mfma_f32_16x16x32_bf16 v[36:39], v[148:151], v[172:175], v[36:39]
	v_mfma_f32_16x16x32_bf16 v[20:23], v[148:151], v[206:209], v[20:23]
	v_mfma_f32_16x16x32_bf16 v[16:19], v[156:159], v[206:209], v[16:19]
	v_mfma_f32_16x16x32_bf16 v[0:3], v[156:159], v[214:217], v[0:3]
	v_mfma_f32_16x16x32_bf16 v[4:7], v[148:151], v[214:217], v[4:7]
	s_setprio 0
	s_barrier
	s_add_i32 s62, 0, 0x18000
	s_add_i32 s63, 0, 0x1c000
	v_add_u32_e32 v140, s62, v199
	v_add_u32_e32 v156, s63, v199
	ds_read_b128 v[120:123], v140
	ds_read_b128 v[124:127], v140 offset:1024
	ds_read_b128 v[132:135], v140 offset:2048
	ds_read_b128 v[140:143], v140 offset:3072
	ds_read_b128 v[144:147], v156
	ds_read_b128 v[148:151], v156 offset:1024
	ds_read_b128 v[152:155], v156 offset:2048
	ds_read_b128 v[156:159], v156 offset:3072
	s_add_u32 s38, s38, 0x100000
	s_addc_u32 s39, s39, 0
	s_mov_b32 m0, s45
	v_lshl_add_u64 v[224:225], s[38:39], 0, v[176:177]
	ds_read_b128 v[160:163], v203 offset:32768
	ds_read_b128 v[164:167], v203 offset:33792
	ds_read_b128 v[168:171], v203 offset:34816
	ds_read_b128 v[172:175], v203 offset:35840
	ds_read_b128 v[192:195], v203 offset:36864
	ds_read_b128 v[206:209], v203 offset:37888
	ds_read_b128 v[210:213], v203 offset:38912
	ds_read_b128 v[214:217], v203 offset:39936
	global_load_lds_dwordx4 v[224:225], off
	v_lshl_add_u64 v[224:225], s[38:39], 0, v[180:181]
	s_mov_b32 m0, s46
	s_nop 0
	global_load_lds_dwordx4 v[224:225], off
	s_waitcnt vmcnt(8)
	s_waitcnt lgkmcnt(0)
	s_barrier
	s_setprio 1
	s_waitcnt lgkmcnt(0)
	v_mfma_f32_16x16x32_bf16 v[136:139], v[120:123], v[160:163], v[136:139]
	v_mfma_f32_16x16x32_bf16 v[128:131], v[132:135], v[160:163], v[128:131]
	v_mfma_f32_16x16x32_bf16 v[104:107], v[132:135], v[168:171], v[104:107]
	v_mfma_f32_16x16x32_bf16 v[108:111], v[120:123], v[168:171], v[108:111]
	v_mfma_f32_16x16x32_bf16 v[92:95], v[120:123], v[192:195], v[92:95]
	v_mfma_f32_16x16x32_bf16 v[88:91], v[132:135], v[192:195], v[88:91]
	v_mfma_f32_16x16x32_bf16 v[72:75], v[132:135], v[210:213], v[72:75]
	v_mfma_f32_16x16x32_bf16 v[76:79], v[120:123], v[210:213], v[76:79]
	v_mfma_f32_16x16x32_bf16 v[136:139], v[124:127], v[164:167], v[136:139]
	v_mfma_f32_16x16x32_bf16 v[128:131], v[140:143], v[164:167], v[128:131]
	v_mfma_f32_16x16x32_bf16 v[104:107], v[140:143], v[172:175], v[104:107]
	v_mfma_f32_16x16x32_bf16 v[108:111], v[124:127], v[172:175], v[108:111]
	v_mfma_f32_16x16x32_bf16 v[92:95], v[124:127], v[206:209], v[92:95]
	v_mfma_f32_16x16x32_bf16 v[88:91], v[140:143], v[206:209], v[88:91]
	v_mfma_f32_16x16x32_bf16 v[72:75], v[140:143], v[214:217], v[72:75]
	v_mfma_f32_16x16x32_bf16 v[76:79], v[124:127], v[214:217], v[76:79]
	s_setprio 0
	s_setprio 1
	v_mfma_f32_16x16x32_bf16 v[116:119], v[144:147], v[160:163], v[116:119]
	v_mfma_f32_16x16x32_bf16 v[112:115], v[152:155], v[160:163], v[112:115]
	v_mfma_f32_16x16x32_bf16 v[96:99], v[152:155], v[168:171], v[96:99]
	v_mfma_f32_16x16x32_bf16 v[100:103], v[144:147], v[168:171], v[100:103]
	v_mfma_f32_16x16x32_bf16 v[84:87], v[144:147], v[192:195], v[84:87]
	v_mfma_f32_16x16x32_bf16 v[80:83], v[152:155], v[192:195], v[80:83]
	v_mfma_f32_16x16x32_bf16 v[64:67], v[152:155], v[210:213], v[64:67]
	v_mfma_f32_16x16x32_bf16 v[68:71], v[144:147], v[210:213], v[68:71]
	v_mfma_f32_16x16x32_bf16 v[116:119], v[148:151], v[164:167], v[116:119]
	v_mfma_f32_16x16x32_bf16 v[112:115], v[156:159], v[164:167], v[112:115]
	v_mfma_f32_16x16x32_bf16 v[96:99], v[156:159], v[172:175], v[96:99]
	v_mfma_f32_16x16x32_bf16 v[100:103], v[148:151], v[172:175], v[100:103]
	v_mfma_f32_16x16x32_bf16 v[84:87], v[148:151], v[206:209], v[84:87]
	v_mfma_f32_16x16x32_bf16 v[80:83], v[156:159], v[206:209], v[80:83]
	v_mfma_f32_16x16x32_bf16 v[64:67], v[156:159], v[214:217], v[64:67]
	v_mfma_f32_16x16x32_bf16 v[68:71], v[148:151], v[214:217], v[68:71]
	s_setprio 0
	s_barrier
; #define PG8_STAGE(bufoff, gbase, voff) do { _Pragma("unroll") for (int _i = 0; _i < 2; ++_i) \
;         __builtin_amdgcn_global_load_lds((const unsigned*)((const char*)(gbase) + (voff)[_i]), (LAS unsigned*)(lds + (bufoff) + ldsw + _i * 8192), 16, 0, 0); } while (0)
; #define PG8_LDA(dst, b, h) do { _Pragma("unroll") for (int m = 0; m < 4; ++m) _Pragma("unroll") for (int k = 0; k < 2; ++k) dst[m][k] = *(const LAS bf16x8*)(lds + PG8_SA(b, h) + aoff + m * 2048 + k * 1024); } while (0)
; #define PG8_MMA(ai, bj, At, Bt) do { __builtin_amdgcn_s_setprio(1); _Pragma("unroll") for (int m = 0; m < 4; ++m) _Pragma("unroll") for (int n = 0; n < 2; ++n) _Pragma("unroll") for (int k = 0; k < 2; ++k) \
;         acc[ai][bj][m][n] = __builtin_amdgcn_mfma_f32_16x16x32_bf16(Bt[n][k], At[m][k], acc[ai][bj][m][n], 0, 0, 0); __builtin_amdgcn_s_setprio(0); } while (0)
; #define PG8_WAIT_V(n) asm volatile("s_waitcnt vmcnt(" #n ")" ::: "memory")
; #define PG8_WAIT_L(n) asm volatile("s_waitcnt lgkmcnt(" #n ")" ::: "memory")
; #define PG8_BAR __builtin_amdgcn_s_barrier()
; #define PG8_SCHED __builtin_amdgcn_sched_barrier(0)
; template <class Epi, class Sched, bool ALIGN_EPI = true, bool SP2 = true>
; __device__ __forceinline__ void gemm_phase(LAS unsigned char* lds, const Gemm g, const Sched& S, const Epi& E) {
;     ...
;             PG8_LDA(At, 1, 1); PG8_STAGE(PG8_SB(1, 0), b3, voffB); PG8_STAGE(PG8_SB(1, 1), b3 + hstep, voffB); PG8_STAGE(PG8_SA(1, 0), a3, voffA);
;             PG8_WAIT_V(8); PG8_WAIT_L(0); PG8_BAR; PG8_MMA(1, 0, At, B0); PG8_MMA(1, 1, At, B1); PG8_BAR; PG8_SCHED;
;     ...
;         if constexpr (ALIGN_EPI) { if (wr == 0) PG8_BAR; }
	s_add_i32 s38, s62, s42
	v_lshl_add_u64 v[196:197], v[196:197], 0, s[14:15]
	s_mov_b32 m0, s38
	ds_read_b128 v[160:163], v203 offset:49152
	ds_read_b128 v[164:167], v203 offset:50176
	ds_read_b128 v[168:171], v203 offset:51200
	ds_read_b128 v[172:175], v203 offset:52224
	ds_read_b128 v[192:195], v203 offset:53248
	ds_read_b128 v[206:209], v203 offset:54272
	ds_read_b128 v[210:213], v203 offset:55296
	ds_read_b128 v[214:217], v203 offset:56320
	global_load_lds_dwordx4 v[196:197], off
	s_add_i32 m0, s38, 0x2000
	s_add_u32 s36, s36, 0x100080
	v_lshl_add_u64 v[196:197], v[218:219], 0, s[14:15]
	s_addc_u32 s37, s37, 0
	s_add_i32 s38, s63, s42
	global_load_lds_dwordx4 v[196:197], off
	v_lshl_add_u64 v[196:197], s[36:37], 0, v[178:179]
	s_mov_b32 m0, s38
	s_nop 0
	global_load_lds_dwordx4 v[196:197], off
	v_lshl_add_u64 v[196:197], s[36:37], 0, v[182:183]
	s_add_i32 m0, s38, 0x2000
	s_nop 0
	global_load_lds_dwordx4 v[196:197], off
	v_lshl_add_u64 v[196:197], v[220:221], 0, s[14:15]
	s_mov_b32 m0, s48
	s_nop 0
	global_load_lds_dwordx4 v[196:197], off
	v_lshl_add_u64 v[196:197], v[222:223], 0, s[14:15]
	s_mov_b32 m0, s49
	s_nop 0
	global_load_lds_dwordx4 v[196:197], off
	s_waitcnt vmcnt(8)
	s_waitcnt lgkmcnt(0)
	s_barrier
	s_setprio 1
	s_waitcnt lgkmcnt(0)
	v_mfma_f32_16x16x32_bf16 v[60:63], v[120:123], v[160:163], v[60:63]
	v_mfma_f32_16x16x32_bf16 v[56:59], v[132:135], v[160:163], v[56:59]
	v_mfma_f32_16x16x32_bf16 v[40:43], v[132:135], v[168:171], v[40:43]
	v_mfma_f32_16x16x32_bf16 v[44:47], v[120:123], v[168:171], v[44:47]
	v_mfma_f32_16x16x32_bf16 v[28:31], v[120:123], v[192:195], v[28:31]
	v_mfma_f32_16x16x32_bf16 v[24:27], v[132:135], v[192:195], v[24:27]
	v_mfma_f32_16x16x32_bf16 v[8:11], v[132:135], v[210:213], v[8:11]
	v_mfma_f32_16x16x32_bf16 v[12:15], v[120:123], v[210:213], v[12:15]
	v_mfma_f32_16x16x32_bf16 v[60:63], v[124:127], v[164:167], v[60:63]
	v_mfma_f32_16x16x32_bf16 v[56:59], v[140:143], v[164:167], v[56:59]
	v_mfma_f32_16x16x32_bf16 v[40:43], v[140:143], v[172:175], v[40:43]
	v_mfma_f32_16x16x32_bf16 v[44:47], v[124:127], v[172:175], v[44:47]
	v_mfma_f32_16x16x32_bf16 v[28:31], v[124:127], v[206:209], v[28:31]
	v_mfma_f32_16x16x32_bf16 v[24:27], v[140:143], v[206:209], v[24:27]
	v_mfma_f32_16x16x32_bf16 v[8:11], v[140:143], v[214:217], v[8:11]
	v_mfma_f32_16x16x32_bf16 v[12:15], v[124:127], v[214:217], v[12:15]
	s_setprio 0
	s_setprio 1
	v_mfma_f32_16x16x32_bf16 v[52:55], v[144:147], v[160:163], v[52:55]
	v_mfma_f32_16x16x32_bf16 v[48:51], v[152:155], v[160:163], v[48:51]
	v_mfma_f32_16x16x32_bf16 v[32:35], v[152:155], v[168:171], v[32:35]
	v_mfma_f32_16x16x32_bf16 v[36:39], v[144:147], v[168:171], v[36:39]
	v_mfma_f32_16x16x32_bf16 v[20:23], v[144:147], v[192:195], v[20:23]
	v_mfma_f32_16x16x32_bf16 v[16:19], v[152:155], v[192:195], v[16:19]
	v_mfma_f32_16x16x32_bf16 v[0:3], v[152:155], v[210:213], v[0:3]
	v_mfma_f32_16x16x32_bf16 v[4:7], v[144:147], v[210:213], v[4:7]
	v_mfma_f32_16x16x32_bf16 v[52:55], v[148:151], v[164:167], v[52:55]
	v_mfma_f32_16x16x32_bf16 v[48:51], v[156:159], v[164:167], v[48:51]
	v_mfma_f32_16x16x32_bf16 v[32:35], v[156:159], v[172:175], v[32:35]
	v_mfma_f32_16x16x32_bf16 v[36:39], v[148:151], v[172:175], v[36:39]
	v_mfma_f32_16x16x32_bf16 v[20:23], v[148:151], v[206:209], v[20:23]
	v_mfma_f32_16x16x32_bf16 v[16:19], v[156:159], v[206:209], v[16:19]
	v_mfma_f32_16x16x32_bf16 v[0:3], v[156:159], v[214:217], v[0:3]
	v_mfma_f32_16x16x32_bf16 v[4:7], v[148:151], v[214:217], v[4:7]
	s_setprio 0
	s_barrier
	s_add_i32 s61, s61, 2
	s_add_u32 s34, s34, 0x100
	s_addc_u32 s35, s35, 0
	s_add_u32 s59, s59, 0x100
	s_addc_u32 s60, s60, 0
	s_cmp_gt_u32 s61, 61
	s_cbranch_scc0 .LBB0_2179
	s_and_b64 vcc, exec, s[16:17]
	s_cbranch_vccz .LBB0_2182
	s_barrier
